# hand-written SSD march phase: 2 barriers per chunk, pipelined LDS reads, transposed y/S epilogues, scan off the critical path
# speedup vs baseline: 1.0423x; 1.0423x over previous
.LBB0_245:
	s_andn2_b64 vcc, exec, s[4:5]
	s_cbranch_vccnz .LBB0_310
	v_readlane_b32 s4, v253, 14
	v_mov_b32_e32 v1, v175
	v_readlane_b32 s5, v253, 15
	s_andn2_b64 vcc, exec, s[4:5]
	v_readfirstlane_b32 s3, v1
	s_cbranch_vccnz .LBB0_310
	v_writelane_b32 v255, s96, 7
	v_writelane_b32 v255, s97, 8
	v_writelane_b32 v255, s98, 9
	v_writelane_b32 v255, s99, 10
	v_writelane_b32 v255, s86, 0
	v_writelane_b32 v255, s87, 1
	v_writelane_b32 v255, s42, 11
	v_writelane_b32 v255, s43, 12
	v_lshrrev_b32_e32 v1, 6, v175
	s_lshl_b32 s4, s42, 8
	v_readfirstlane_b32 s3, v1
	s_add_u32 s56, s94, s4
	s_addc_u32 s57, s95, 0
	v_readlane_b32 s58, v253, 3
	v_readlane_b32 s61, v253, 5
	s_movk_i32 s59, 0x110
	s_movk_i32 s60, 0x50
	s_nop 3
.Lm_item:
	s_barrier
	s_and_b32 s4, s61, 7
	s_lshr_b32 s5, s61, 3
	s_lshr_b32 s6, s5, 3
	s_lshl_b32 s4, s4, 2
	s_add_u32 s4, s4, s6
	s_and_b32 s5, s5, 7
	s_lshr_b32 s6, s4, 4
	s_bfe_u32 s7, s4, 0x30001
	s_and_b32 s51, s4, 1
	s_lshr_b32 s8, s5, 1
	s_lshl_b32 s9, s7, 2
	s_add_u32 s8, s9, s8
	s_and_b32 s5, s5, 1
	s_lshl_b32 s9, s51, 5
	s_add_u32 s9, s9, s8
	s_lshl_b32 s9, s9, 2
	s_load_dword s10, s[56:57], s9
	s_mov_b32 s55, 0
	s_mov_b32 s46, 0x10000
	s_mov_b32 s47, 0x2000
	s_mov_b32 s48, 0x8000
	s_mov_b32 s49, 0x80000
	s_mov_b32 s11, 0
	s_cmp_eq_u32 s51, 0
	s_cbranch_scc1 .Lm_fwd_1
	s_mov_b32 s55, -1
	s_sub_u32 s46, 0, s46
	s_sub_u32 s47, 0, s47
	s_sub_u32 s48, 0, s48
	s_sub_u32 s49, 0, s49
	s_mov_b32 s11, 63
.Lm_fwd_1:
	s_lshl_b32 s15, s7, 23
	s_lshl_b32 s96, s6, 22
	s_add_u32 s15, s15, s96
	s_lshl_b32 s96, s11, 16
	s_add_u32 s15, s15, s96
	s_add_u32 s15, s15, 0x1b000000
	s_add_u32 s38, s36, s15
	s_addc_u32 s39, s37, 0
	s_lshl_b32 s15, s8, 1
	s_add_u32 s15, s15, s5
	s_lshl_b32 s15, s15, 20
	s_lshl_b32 s96, s6, 19
	s_add_u32 s15, s15, s96
	s_lshl_b32 s96, s11, 13
	s_add_u32 s15, s15, s96
	s_add_u32 s15, s15, 0x17000000
	s_add_u32 s40, s36, s15
	s_addc_u32 s41, s37, 0
	s_lshl_b32 s15, s6, 21
	s_add_u32 s15, s15, s9
	s_lshl_b32 s96, s11, 15
	s_add_u32 s15, s15, s96
	s_add_u32 s15, s15, 0x1f000000
	s_add_u32 s42, s36, s15
	s_addc_u32 s43, s37, 0
	s_lshl_b32 s15, s6, 25
	s_lshl_b32 s96, s8, 7
	s_add_u32 s15, s15, s96
	s_lshl_b32 s96, s5, 6
	s_add_u32 s15, s15, s96
	s_lshl_b32 s96, s11, 19
	s_add_u32 s15, s15, s96
	s_lshl_b32 s96, s51, 26
	s_add_u32 s15, s15, s96
	s_add_u32 s15, s15, 0xf000000
	s_add_u32 s44, s36, s15
	s_addc_u32 s45, s37, 0
	s_lshl_b32 s4, s3, 2
	s_lshr_b32 s5, 0x2101233, s4
	s_and_b32 s5, s5, 3
	s_lshr_b32 s6, 0x2001020, s4
	s_and_b32 s6, s6, 3
	s_lshr_b32 s7, 0x1111222, s4
	s_and_b32 s52, s7, 3
	s_sub_i32 s8, 3, s5
	s_cmp_eq_u32 s52, 2
	s_cselect_b32 s97, 2, 3
	s_sub_i32 s97, s97, s6
	s_cmp_eq_u32 s51, 0
	s_cselect_b32 s13, s5, s8
	s_cselect_b32 s14, s6, s97
	s_cmp_eq_u32 s14, s13
	s_cselect_b32 s53, 1, 0
	s_add_u32 s4, s14, 1
	s_cmp_eq_u32 s4, s13
	s_cselect_b32 s54, 1, 0
	s_waitcnt lgkmcnt(0)
	v_mov_b32_e32 v1, s10
	v_mul_f32_e32 v1, 0x3fb8aa3b, v1
	v_exp_f32_e32 v1, v1
	s_nop 0
	v_xor_b32_e32 v1, 0x80000000, v1
	s_nop 0
	v_readfirstlane_b32 s62, v1
	v_and_b32_e32 v116, 31, v175
	v_bfe_u32 v117, v175, 5, 1
	v_bfe_u32 v118, v175, 2, 2
	v_and_b32_e32 v119, 3, v175
	v_bfe_u32 v120, v175, 4, 1
	v_and_b32_e32 v121, 63, v175
	v_lshlrev_b32_e32 v122, 5, v120
	v_lshl_add_u32 v122, v119, 3, v122
	v_lshl_add_u32 v123, v117, 3, v118
	v_lshrrev_b32_e32 v124, 4, v175
	v_and_b32_e32 v125, 15, v175
	v_lshlrev_b32_e32 v125, 4, v125
	v_lshl_add_u32 v164, v124, 9, v125
	v_add_u32_e32 v165, 0x4000, v164
	v_add_u32_e32 v166, 0x8000, v164
	v_add_u32_e32 v167, 0xc000, v164
	v_mad_u32_u24 v169, v124, s59, v125
	v_lshlrev_b32_e32 v168, 4, v175
	v_lshrrev_b32_e32 v126, 2, v175
	v_lshlrev_b32_e32 v127, 4, v119
	v_mad_u32_u24 v127, v126, s60, v127
	v_add_u32_e32 v170, 0x19800, v127
	v_lshlrev_b32_e32 v127, 2, v126
	v_add_u32_e32 v171, 0x23000, v127
	v_mov_b32_e32 v172, 0x23400
	s_lshl_b32 s4, s3, 5
	v_add_u32_e32 v128, s4, v116
	v_lshlrev_b32_e32 v129, 4, v117
	v_mad_u32_u24 v173, v128, s59, v129
	v_mad_u32_u24 v130, v116, s59, v129
	v_add_u32_e32 v210, 0x1e800, v130
	v_lshlrev_b32_e32 v130, 2, v128
	v_add_u32_e32 v211, 0x23000, v130
	v_lshlrev_b32_e32 v130, 3, v117
	v_lshl_add_u32 v212, v128, 12, v130
	v_mad_u32_u24 v130, v123, s60, v122
	v_add_u32_e32 v208, 0x19800, v130
	v_add_u32_e32 v192, 0x1c000, v130
	v_mad_u32_u24 v131, v123, s59, v122
	s_lshl_b32 s4, s3, 6
	v_add_u32_e32 v130, s4, v131
	v_add_u32_e32 v209, 0x11000, v130
	s_sub_i32 s4, s3, 4
	s_lshl_b32 s4, s4, 6
	v_add_u32_e32 v130, s4, v131
	v_add_u32_e32 v193, 0x8800, v130
	v_lshlrev_b32_e32 v130, 3, v117
	v_mad_u32_u24 v130, v116, s59, v130
	v_add_u32_e32 v130, s4, v130
	v_add_u32_e32 v194, 0x1e800, v130
	v_lshlrev_b32_e32 v195, 9, v121
	v_lshlrev_b32_e32 v130, 3, v121
	v_add_u32_e32 v196, 0x23000, v130
	v_subrev_u32_e32 v130, 1, v121
	v_max_i32_e32 v130, 0, v130
	v_lshlrev_b32_e32 v197, 2, v130
	v_cmp_le_u32_e64 s[16:17], 1, v121
	v_subrev_u32_e32 v130, 2, v121
	v_max_i32_e32 v130, 0, v130
	v_lshlrev_b32_e32 v198, 2, v130
	v_cmp_le_u32_e64 s[18:19], 2, v121
	v_subrev_u32_e32 v130, 4, v121
	v_max_i32_e32 v130, 0, v130
	v_lshlrev_b32_e32 v199, 2, v130
	v_cmp_le_u32_e64 s[20:21], 4, v121
	v_subrev_u32_e32 v130, 8, v121
	v_max_i32_e32 v130, 0, v130
	v_lshlrev_b32_e32 v200, 2, v130
	v_cmp_le_u32_e64 s[22:23], 8, v121
	v_subrev_u32_e32 v130, 16, v121
	v_max_i32_e32 v130, 0, v130
	v_lshlrev_b32_e32 v201, 2, v130
	v_cmp_le_u32_e64 s[24:25], 16, v121
	v_subrev_u32_e32 v130, 32, v121
	v_max_i32_e32 v130, 0, v130
	v_lshlrev_b32_e32 v202, 2, v130
	v_cmp_le_u32_e64 s[26:27], 32, v121
	v_mov_b32_e32 v225, 0xfc
	s_lshl_b32 s4, s13, 5
	v_add_u32_e32 v130, s4, v116
	v_mad_u32_u24 v216, v130, s59, v129
	s_lshl_b32 s5, s14, 5
	v_add_u32_e32 v131, s5, v116
	v_mad_u32_u24 v217, v131, s59, v129
	s_lshl_b32 s6, s13, 7
	s_add_u32 s6, s6, 0x23000
	v_add_u32_e32 v222, s6, v129
	v_lshlrev_b32_e32 v130, 2, v131
	v_add_u32_e32 v223, 0x23000, v130
	v_lshlrev_b32_e32 v130, 3, v117
	v_mad_u32_u24 v130, v131, s59, v130
	s_lshl_b32 s6, s13, 6
	s_add_u32 s6, s6, 0x11000
	v_add_u32_e32 v224, s6, v130
	v_lshlrev_b32_e32 v129, 2, v117
	s_cmp_eq_u32 s51, 0
	s_cbranch_scc0 .Lm_mbwd_2
	v_add_u32_e32 v130, 0, v129
	v_cmp_le_u32_e64 s[64:65], v116, v130
	v_add_u32_e32 v130, 1, v129
	v_cmp_le_u32_e64 s[66:67], v116, v130
	v_add_u32_e32 v130, 2, v129
	v_cmp_le_u32_e64 s[68:69], v116, v130
	v_add_u32_e32 v130, 3, v129
	v_cmp_le_u32_e64 s[70:71], v116, v130
	v_add_u32_e32 v130, 8, v129
	v_cmp_le_u32_e64 s[72:73], v116, v130
	v_add_u32_e32 v130, 9, v129
	v_cmp_le_u32_e64 s[74:75], v116, v130
	v_add_u32_e32 v130, 10, v129
	v_cmp_le_u32_e64 s[76:77], v116, v130
	v_add_u32_e32 v130, 11, v129
	v_cmp_le_u32_e64 s[78:79], v116, v130
	v_add_u32_e32 v130, 16, v129
	v_cmp_le_u32_e64 s[80:81], v116, v130
	v_add_u32_e32 v130, 17, v129
	v_cmp_le_u32_e64 s[82:83], v116, v130
	v_add_u32_e32 v130, 18, v129
	v_cmp_le_u32_e64 s[84:85], v116, v130
	v_add_u32_e32 v130, 19, v129
	v_cmp_le_u32_e64 s[86:87], v116, v130
	v_add_u32_e32 v130, 24, v129
	v_cmp_le_u32_e64 s[88:89], v116, v130
	v_add_u32_e32 v130, 25, v129
	v_cmp_le_u32_e64 s[90:91], v116, v130
	v_add_u32_e32 v130, 26, v129
	v_cmp_le_u32_e64 s[92:93], v116, v130
	v_add_u32_e32 v130, 27, v129
	v_cmp_le_u32_e64 s[94:95], v116, v130
	s_branch .Lm_mdone_3
.Lm_mbwd_2:
	v_add_u32_e32 v130, 0, v129
	v_cmp_ge_u32_e64 s[64:65], v116, v130
	v_add_u32_e32 v130, 1, v129
	v_cmp_ge_u32_e64 s[66:67], v116, v130
	v_add_u32_e32 v130, 2, v129
	v_cmp_ge_u32_e64 s[68:69], v116, v130
	v_add_u32_e32 v130, 3, v129
	v_cmp_ge_u32_e64 s[70:71], v116, v130
	v_add_u32_e32 v130, 8, v129
	v_cmp_ge_u32_e64 s[72:73], v116, v130
	v_add_u32_e32 v130, 9, v129
	v_cmp_ge_u32_e64 s[74:75], v116, v130
	v_add_u32_e32 v130, 10, v129
	v_cmp_ge_u32_e64 s[76:77], v116, v130
	v_add_u32_e32 v130, 11, v129
	v_cmp_ge_u32_e64 s[78:79], v116, v130
	v_add_u32_e32 v130, 16, v129
	v_cmp_ge_u32_e64 s[80:81], v116, v130
	v_add_u32_e32 v130, 17, v129
	v_cmp_ge_u32_e64 s[82:83], v116, v130
	v_add_u32_e32 v130, 18, v129
	v_cmp_ge_u32_e64 s[84:85], v116, v130
	v_add_u32_e32 v130, 19, v129
	v_cmp_ge_u32_e64 s[86:87], v116, v130
	v_add_u32_e32 v130, 24, v129
	v_cmp_ge_u32_e64 s[88:89], v116, v130
	v_add_u32_e32 v130, 25, v129
	v_cmp_ge_u32_e64 s[90:91], v116, v130
	v_add_u32_e32 v130, 26, v129
	v_cmp_ge_u32_e64 s[92:93], v116, v130
	v_add_u32_e32 v130, 27, v129
	v_cmp_ge_u32_e64 s[94:95], v116, v130
.Lm_mdone_3:
	v_lshlrev_b32_e32 v130, 4, v175
	v_add_u32_e32 v130, 0x11000, v130
	ds_write_b128 v130, v[112:115] offset:0
	ds_write_b128 v130, v[112:115] offset:8192
	ds_write_b128 v130, v[112:115] offset:16384
	ds_write_b128 v130, v[112:115] offset:24576
	ds_write_b128 v130, v[112:115] offset:32768
	ds_write_b128 v130, v[112:115] offset:40960
	ds_write_b128 v130, v[112:115] offset:49152
	ds_write_b128 v130, v[112:115] offset:57344
	v_mov_b32_e32 v176, 0
	v_mov_b32_e32 v177, 0
	v_mov_b32_e32 v178, 0
	v_mov_b32_e32 v179, 0
	v_mov_b32_e32 v180, 0
	v_mov_b32_e32 v181, 0
	v_mov_b32_e32 v182, 0
	v_mov_b32_e32 v183, 0
	v_mov_b32_e32 v184, 0
	v_mov_b32_e32 v185, 0
	v_mov_b32_e32 v186, 0
	v_mov_b32_e32 v187, 0
	v_mov_b32_e32 v188, 0
	v_mov_b32_e32 v189, 0
	v_mov_b32_e32 v190, 0
	v_mov_b32_e32 v191, 0
	s_cmp_eq_u32 s3, 7
	s_cbranch_scc0 .Lm_pro_w7_4
	global_load_dword v204, v195, s[42:43]
	global_load_dword v205, v195, s[42:43] offset:256
	s_add_u32 s42, s42, s48
	s_addc_u32 s43, s43, s55
.Lm_pro_w7_4:
	global_load_dwordx4 v[4:7], v164, s[38:39]
	global_load_dwordx4 v[20:23], v164, s[38:39] offset:256
	global_load_dwordx4 v[8:11], v165, s[38:39]
	global_load_dwordx4 v[24:27], v165, s[38:39] offset:256
	global_load_dwordx4 v[12:15], v166, s[38:39]
	global_load_dwordx4 v[28:31], v166, s[38:39] offset:256
	global_load_dwordx4 v[16:19], v167, s[38:39]
	global_load_dwordx4 v[32:35], v167, s[38:39] offset:256
	global_load_dwordx4 v[36:39], v168, s[40:41]
	s_add_u32 s38, s38, s46
	s_addc_u32 s39, s39, s55
	s_add_u32 s40, s40, s47
	s_addc_u32 s41, s41, s55
	global_load_dwordx4 v[40:43], v164, s[38:39]
	global_load_dwordx4 v[56:59], v164, s[38:39] offset:256
	global_load_dwordx4 v[44:47], v165, s[38:39]
	global_load_dwordx4 v[60:63], v165, s[38:39] offset:256
	global_load_dwordx4 v[48:51], v166, s[38:39]
	global_load_dwordx4 v[64:67], v166, s[38:39] offset:256
	global_load_dwordx4 v[52:55], v167, s[38:39]
	global_load_dwordx4 v[68:71], v167, s[38:39] offset:256
	global_load_dwordx4 v[72:75], v168, s[40:41]
	s_add_u32 s38, s38, s46
	s_addc_u32 s39, s39, s55
	s_add_u32 s40, s40, s47
	s_addc_u32 s41, s41, s55
	s_cmp_eq_u32 s3, 7
	s_cbranch_scc0 .Lm_pro_w7e_5
	s_waitcnt vmcnt(18)
	v_mul_f32_e32 v116, s62, v204
	v_mul_f32_e32 v117, s62, v205
	v_add_f32_e32 v118, v116, v117
	ds_bpermute_b32 v119, v197, v118
	s_waitcnt lgkmcnt(0)
	v_add_f32_e32 v119, v118, v119
	v_cndmask_b32_e64 v118, v118, v119, s[16:17]
	ds_bpermute_b32 v119, v198, v118
	s_waitcnt lgkmcnt(0)
	v_add_f32_e32 v119, v118, v119
	v_cndmask_b32_e64 v118, v118, v119, s[18:19]
	ds_bpermute_b32 v119, v199, v118
	s_waitcnt lgkmcnt(0)
	v_add_f32_e32 v119, v118, v119
	v_cndmask_b32_e64 v118, v118, v119, s[20:21]
	ds_bpermute_b32 v119, v200, v118
	s_waitcnt lgkmcnt(0)
	v_add_f32_e32 v119, v118, v119
	v_cndmask_b32_e64 v118, v118, v119, s[22:23]
	ds_bpermute_b32 v119, v201, v118
	s_waitcnt lgkmcnt(0)
	v_add_f32_e32 v119, v118, v119
	v_cndmask_b32_e64 v118, v118, v119, s[24:25]
	ds_bpermute_b32 v119, v202, v118
	s_waitcnt lgkmcnt(0)
	v_add_f32_e32 v119, v118, v119
	v_cndmask_b32_e64 v118, v118, v119, s[26:27]
	ds_bpermute_b32 v120, v225, v118
	v_sub_f32_e32 v122, v118, v117
	v_mov_b32_e32 v123, v118
	s_waitcnt lgkmcnt(0)
	s_cmp_eq_u32 s51, 0
	s_cbranch_scc1 .Lm_scanf_6
	v_sub_f32_e32 v122, v120, v122
	v_sub_f32_e32 v123, v120, v123
	v_fma_f32 v122, v204, s62, v122
	v_fma_f32 v123, v205, s62, v123
.Lm_scanf_6:
	v_mul_f32_e32 v122, 0x3fb8aa3b, v122
	v_mul_f32_e32 v123, 0x3fb8aa3b, v123
	v_mul_f32_e32 v120, 0x3fb8aa3b, v120
	ds_write_b64 v196, v[122:123] offset:0
	ds_write_b64 v196, v[204:205] offset:512
	ds_write_b32 v172, v120 offset:0
	s_waitcnt lgkmcnt(0)
	global_load_dword v204, v195, s[42:43]
	global_load_dword v205, v195, s[42:43] offset:256
	s_add_u32 s42, s42, s48
	s_addc_u32 s43, s43, s55
.Lm_pro_w7e_5:
	s_waitcnt lgkmcnt(0)
	s_barrier
	s_waitcnt vmcnt(9)
	ds_read_b32 v116, v172 offset:0
	ds_read_b32 v117, v171 offset:0
	ds_read_b32 v118, v171 offset:512
	ds_write_b128 v169, v[20:23] offset:0
	ds_write_b128 v169, v[4:7] offset:34816
	ds_write_b128 v169, v[24:27] offset:8704
	ds_write_b128 v169, v[8:11] offset:43520
	ds_write_b128 v169, v[28:31] offset:17408
	ds_write_b128 v169, v[12:15] offset:52224
	ds_write_b128 v169, v[32:35] offset:26112
	ds_write_b128 v169, v[16:19] offset:60928
	v_lshlrev_b32_e32 v120, 16, v36
	v_and_b32_e32 v121, 0xffff0000, v36
	v_lshlrev_b32_e32 v122, 16, v37
	v_and_b32_e32 v123, 0xffff0000, v37
	v_lshlrev_b32_e32 v124, 16, v38
	v_and_b32_e32 v125, 0xffff0000, v38
	v_lshlrev_b32_e32 v126, 16, v39
	v_and_b32_e32 v127, 0xffff0000, v39
	s_waitcnt lgkmcnt(8)
	v_sub_f32_e32 v119, v116, v117
	v_exp_f32_e32 v119, v119
	v_mul_f32_e32 v128, v118, v120
	v_mul_f32_e32 v129, v118, v121
	v_mul_f32_e32 v130, v118, v122
	v_mul_f32_e32 v131, v118, v123
	v_mul_f32_e32 v132, v118, v124
	v_mul_f32_e32 v133, v118, v125
	v_mul_f32_e32 v134, v118, v126
	v_mul_f32_e32 v135, v118, v127
	v_mul_f32_e32 v119, v118, v119
	v_cvt_pk_bf16_f32 v144, v128, v129
	v_cvt_pk_bf16_f32 v145, v130, v131
	v_cvt_pk_bf16_f32 v146, v132, v133
	v_cvt_pk_bf16_f32 v147, v134, v135
	v_mul_f32_e32 v136, v119, v120
	v_mul_f32_e32 v137, v119, v121
	v_mul_f32_e32 v138, v119, v122
	v_mul_f32_e32 v139, v119, v123
	v_mul_f32_e32 v140, v119, v124
	v_mul_f32_e32 v141, v119, v125
	v_mul_f32_e32 v142, v119, v126
	v_mul_f32_e32 v143, v119, v127
	v_cvt_pk_bf16_f32 v148, v136, v137
	v_cvt_pk_bf16_f32 v149, v138, v139
	v_cvt_pk_bf16_f32 v150, v140, v141
	v_cvt_pk_bf16_f32 v151, v142, v143
	ds_write_b128 v170, v[144:147] offset:0
	ds_write_b128 v170, v[148:151] offset:10240
	s_waitcnt lgkmcnt(0)
	global_load_dwordx4 v[4:7], v164, s[38:39]
	global_load_dwordx4 v[20:23], v164, s[38:39] offset:256
	global_load_dwordx4 v[8:11], v165, s[38:39]
	global_load_dwordx4 v[24:27], v165, s[38:39] offset:256
	global_load_dwordx4 v[12:15], v166, s[38:39]
	global_load_dwordx4 v[28:31], v166, s[38:39] offset:256
	global_load_dwordx4 v[16:19], v167, s[38:39]
	global_load_dwordx4 v[32:35], v167, s[38:39] offset:256
	global_load_dwordx4 v[36:39], v168, s[40:41]
	s_add_u32 s38, s38, s46
	s_addc_u32 s39, s39, s55
	s_add_u32 s40, s40, s47
	s_addc_u32 s41, s41, s55
	s_barrier
	s_mov_b32 s50, 0
.Lm_loop:
	s_cmp_eq_u32 s52, 2
	s_cbranch_scc0 .Lm_g1_7
	ds_read_b128 v[116:119], v216 offset:0
	ds_read_b128 v[120:123], v217 offset:34816
	ds_read_b128 v[124:127], v217 offset:43520
	ds_read_b128 v[128:131], v216 offset:32
	ds_read_b128 v[132:135], v217 offset:34848
	ds_read_b128 v[136:139], v217 offset:43552
	ds_read_b128 v[140:143], v216 offset:64
	ds_read_b128 v[144:147], v217 offset:34880
	ds_read_b128 v[148:151], v217 offset:43584
	ds_read_b128 v[152:155], v216 offset:96
	ds_read_b128 v[156:159], v217 offset:34912
	ds_read_b128 v[160:163], v217 offset:43616
	s_waitcnt lgkmcnt(9)
	v_mfma_f32_32x32x16_bf16 v[76:91], v[116:119], v[120:123], 0
	v_mfma_f32_32x32x16_bf16 v[92:107], v[116:119], v[124:127], 0
	ds_read_b128 v[116:119], v216 offset:128
	ds_read_b128 v[120:123], v217 offset:34944
	ds_read_b128 v[124:127], v217 offset:43648
	s_waitcnt lgkmcnt(9)
	v_mfma_f32_32x32x16_bf16 v[76:91], v[128:131], v[132:135], v[76:91]
	v_mfma_f32_32x32x16_bf16 v[92:107], v[128:131], v[136:139], v[92:107]
	ds_read_b128 v[128:131], v216 offset:160
	ds_read_b128 v[132:135], v217 offset:34976
	ds_read_b128 v[136:139], v217 offset:43680
	s_waitcnt lgkmcnt(9)
	v_mfma_f32_32x32x16_bf16 v[76:91], v[140:143], v[144:147], v[76:91]
	v_mfma_f32_32x32x16_bf16 v[92:107], v[140:143], v[148:151], v[92:107]
	ds_read_b128 v[140:143], v216 offset:192
	ds_read_b128 v[144:147], v217 offset:35008
	ds_read_b128 v[148:151], v217 offset:43712
	s_waitcnt lgkmcnt(9)
	v_mfma_f32_32x32x16_bf16 v[76:91], v[152:155], v[156:159], v[76:91]
	v_mfma_f32_32x32x16_bf16 v[92:107], v[152:155], v[160:163], v[92:107]
	ds_read_b128 v[152:155], v216 offset:224
	ds_read_b128 v[156:159], v217 offset:35040
	ds_read_b128 v[160:163], v217 offset:43744
	s_waitcnt lgkmcnt(9)
	v_mfma_f32_32x32x16_bf16 v[76:91], v[116:119], v[120:123], v[76:91]
	v_mfma_f32_32x32x16_bf16 v[92:107], v[116:119], v[124:127], v[92:107]
	ds_read_b128 v[234:237], v222 offset:0
	ds_read_b128 v[238:241], v222 offset:32
	ds_read_b128 v[242:245], v222 offset:64
	ds_read_b128 v[246:249], v222 offset:96
	ds_read_b32 v250, v223 offset:0
	ds_read_b32 v251, v223 offset:128
	s_waitcnt lgkmcnt(12)
	v_mfma_f32_32x32x16_bf16 v[76:91], v[128:131], v[132:135], v[76:91]
	v_mfma_f32_32x32x16_bf16 v[92:107], v[128:131], v[136:139], v[92:107]
	s_waitcnt lgkmcnt(9)
	v_mfma_f32_32x32x16_bf16 v[76:91], v[140:143], v[144:147], v[76:91]
	v_mfma_f32_32x32x16_bf16 v[92:107], v[140:143], v[148:151], v[92:107]
	s_waitcnt lgkmcnt(6)
	v_mfma_f32_32x32x16_bf16 v[76:91], v[152:155], v[156:159], v[76:91]
	v_mfma_f32_32x32x16_bf16 v[92:107], v[152:155], v[160:163], v[92:107]
	ds_read_b128 v[176:179], v173 offset:0
	ds_read_b128 v[180:183], v173 offset:32
	ds_read_b128 v[184:187], v173 offset:64
	ds_read_b128 v[188:191], v173 offset:96
	ds_read_b128 v[192:195], v173 offset:128
	ds_read_b128 v[196:199], v173 offset:160
	ds_read_b128 v[200:203], v173 offset:192
	ds_read_b128 v[204:207], v173 offset:224
	ds_read_b32 v2, v211 offset:0
	s_waitcnt lgkmcnt(9)
	v_sub_f32_e32 v116, v234, v250
	v_sub_f32_e32 v117, v235, v250
	v_sub_f32_e32 v118, v236, v250
	v_sub_f32_e32 v119, v237, v250
	v_sub_f32_e32 v120, v238, v250
	v_sub_f32_e32 v121, v239, v250
	v_sub_f32_e32 v122, v240, v250
	v_sub_f32_e32 v123, v241, v250
	v_sub_f32_e32 v124, v242, v250
	v_sub_f32_e32 v125, v243, v250
	v_sub_f32_e32 v126, v244, v250
	v_sub_f32_e32 v127, v245, v250
	v_sub_f32_e32 v128, v246, v250
	v_sub_f32_e32 v129, v247, v250
	v_sub_f32_e32 v130, v248, v250
	v_sub_f32_e32 v131, v249, v250
	v_exp_f32_e32 v116, v116
	v_exp_f32_e32 v117, v117
	v_exp_f32_e32 v118, v118
	v_exp_f32_e32 v119, v119
	v_exp_f32_e32 v120, v120
	v_exp_f32_e32 v121, v121
	v_exp_f32_e32 v122, v122
	v_exp_f32_e32 v123, v123
	v_exp_f32_e32 v124, v124
	v_exp_f32_e32 v125, v125
	v_exp_f32_e32 v126, v126
	v_exp_f32_e32 v127, v127
	v_exp_f32_e32 v128, v128
	v_exp_f32_e32 v129, v129
	v_exp_f32_e32 v130, v130
	v_exp_f32_e32 v131, v131
	v_mul_f32_e32 v76, v76, v116
	v_mul_f32_e32 v77, v77, v117
	v_mul_f32_e32 v78, v78, v118
	v_mul_f32_e32 v79, v79, v119
	v_mul_f32_e32 v80, v80, v120
	v_mul_f32_e32 v81, v81, v121
	v_mul_f32_e32 v82, v82, v122
	v_mul_f32_e32 v83, v83, v123
	v_mul_f32_e32 v84, v84, v124
	v_mul_f32_e32 v85, v85, v125
	v_mul_f32_e32 v86, v86, v126
	v_mul_f32_e32 v87, v87, v127
	v_mul_f32_e32 v88, v88, v128
	v_mul_f32_e32 v89, v89, v129
	v_mul_f32_e32 v90, v90, v130
	v_mul_f32_e32 v91, v91, v131
	s_cmp_eq_u32 s53, 0
	s_cbranch_scc1 .Lm_nodiag_12
	v_cndmask_b32_e64 v76, 0, v76, s[64:65]
	v_cndmask_b32_e64 v77, 0, v77, s[66:67]
	v_cndmask_b32_e64 v78, 0, v78, s[68:69]
	v_cndmask_b32_e64 v79, 0, v79, s[70:71]
	v_cndmask_b32_e64 v80, 0, v80, s[72:73]
	v_cndmask_b32_e64 v81, 0, v81, s[74:75]
	v_cndmask_b32_e64 v82, 0, v82, s[76:77]
	v_cndmask_b32_e64 v83, 0, v83, s[78:79]
	v_cndmask_b32_e64 v84, 0, v84, s[80:81]
	v_cndmask_b32_e64 v85, 0, v85, s[82:83]
	v_cndmask_b32_e64 v86, 0, v86, s[84:85]
	v_cndmask_b32_e64 v87, 0, v87, s[86:87]
	v_cndmask_b32_e64 v88, 0, v88, s[88:89]
	v_cndmask_b32_e64 v89, 0, v89, s[90:91]
	v_cndmask_b32_e64 v90, 0, v90, s[92:93]
	v_cndmask_b32_e64 v91, 0, v91, s[94:95]
.Lm_nodiag_12:
	v_cvt_pk_bf16_f32 v132, v76, v77
	v_cvt_pk_bf16_f32 v133, v78, v79
	v_cvt_pk_bf16_f32 v134, v80, v81
	v_cvt_pk_bf16_f32 v135, v82, v83
	v_cvt_pk_bf16_f32 v136, v84, v85
	v_cvt_pk_bf16_f32 v137, v86, v87
	v_cvt_pk_bf16_f32 v138, v88, v89
	v_cvt_pk_bf16_f32 v139, v90, v91
	ds_write_b64 v224, v[132:133] offset:0
	ds_write_b64 v224, v[134:135] offset:16
	ds_write_b64 v224, v[136:137] offset:32
	ds_write_b64 v224, v[138:139] offset:48
	v_sub_f32_e32 v116, v234, v251
	v_sub_f32_e32 v117, v235, v251
	v_sub_f32_e32 v118, v236, v251
	v_sub_f32_e32 v119, v237, v251
	v_sub_f32_e32 v120, v238, v251
	v_sub_f32_e32 v121, v239, v251
	v_sub_f32_e32 v122, v240, v251
	v_sub_f32_e32 v123, v241, v251
	v_sub_f32_e32 v124, v242, v251
	v_sub_f32_e32 v125, v243, v251
	v_sub_f32_e32 v126, v244, v251
	v_sub_f32_e32 v127, v245, v251
	v_sub_f32_e32 v128, v246, v251
	v_sub_f32_e32 v129, v247, v251
	v_sub_f32_e32 v130, v248, v251
	v_sub_f32_e32 v131, v249, v251
	v_exp_f32_e32 v116, v116
	v_exp_f32_e32 v117, v117
	v_exp_f32_e32 v118, v118
	v_exp_f32_e32 v119, v119
	v_exp_f32_e32 v120, v120
	v_exp_f32_e32 v121, v121
	v_exp_f32_e32 v122, v122
	v_exp_f32_e32 v123, v123
	v_exp_f32_e32 v124, v124
	v_exp_f32_e32 v125, v125
	v_exp_f32_e32 v126, v126
	v_exp_f32_e32 v127, v127
	v_exp_f32_e32 v128, v128
	v_exp_f32_e32 v129, v129
	v_exp_f32_e32 v130, v130
	v_exp_f32_e32 v131, v131
	v_mul_f32_e32 v92, v92, v116
	v_mul_f32_e32 v93, v93, v117
	v_mul_f32_e32 v94, v94, v118
	v_mul_f32_e32 v95, v95, v119
	v_mul_f32_e32 v96, v96, v120
	v_mul_f32_e32 v97, v97, v121
	v_mul_f32_e32 v98, v98, v122
	v_mul_f32_e32 v99, v99, v123
	v_mul_f32_e32 v100, v100, v124
	v_mul_f32_e32 v101, v101, v125
	v_mul_f32_e32 v102, v102, v126
	v_mul_f32_e32 v103, v103, v127
	v_mul_f32_e32 v104, v104, v128
	v_mul_f32_e32 v105, v105, v129
	v_mul_f32_e32 v106, v106, v130
	v_mul_f32_e32 v107, v107, v131
	s_cmp_eq_u32 s54, 0
	s_cbranch_scc1 .Lm_nodiag_13
	v_cndmask_b32_e64 v92, 0, v92, s[64:65]
	v_cndmask_b32_e64 v93, 0, v93, s[66:67]
	v_cndmask_b32_e64 v94, 0, v94, s[68:69]
	v_cndmask_b32_e64 v95, 0, v95, s[70:71]
	v_cndmask_b32_e64 v96, 0, v96, s[72:73]
	v_cndmask_b32_e64 v97, 0, v97, s[74:75]
	v_cndmask_b32_e64 v98, 0, v98, s[76:77]
	v_cndmask_b32_e64 v99, 0, v99, s[78:79]
	v_cndmask_b32_e64 v100, 0, v100, s[80:81]
	v_cndmask_b32_e64 v101, 0, v101, s[82:83]
	v_cndmask_b32_e64 v102, 0, v102, s[84:85]
	v_cndmask_b32_e64 v103, 0, v103, s[86:87]
	v_cndmask_b32_e64 v104, 0, v104, s[88:89]
	v_cndmask_b32_e64 v105, 0, v105, s[90:91]
	v_cndmask_b32_e64 v106, 0, v106, s[92:93]
	v_cndmask_b32_e64 v107, 0, v107, s[94:95]
.Lm_nodiag_13:
	v_cvt_pk_bf16_f32 v132, v92, v93
	v_cvt_pk_bf16_f32 v133, v94, v95
	v_cvt_pk_bf16_f32 v134, v96, v97
	v_cvt_pk_bf16_f32 v135, v98, v99
	v_cvt_pk_bf16_f32 v136, v100, v101
	v_cvt_pk_bf16_f32 v137, v102, v103
	v_cvt_pk_bf16_f32 v138, v104, v105
	v_cvt_pk_bf16_f32 v139, v106, v107
	ds_write_b64 v224, v[132:133] offset:8704
	ds_write_b64 v224, v[134:135] offset:8720
	ds_write_b64 v224, v[136:137] offset:8736
	ds_write_b64 v224, v[138:139] offset:8752
	s_branch .Lm_adone_11
.Lm_g1_7:
	s_cmp_eq_u32 s52, 1
	s_cbranch_scc0 .Lm_g0_8
	ds_read_b128 v[116:119], v216 offset:0
	ds_read_b128 v[120:123], v217 offset:34816
	ds_read_b128 v[128:131], v216 offset:32
	ds_read_b128 v[132:135], v217 offset:34848
	ds_read_b128 v[140:143], v216 offset:64
	ds_read_b128 v[144:147], v217 offset:34880
	ds_read_b128 v[152:155], v216 offset:96
	ds_read_b128 v[156:159], v217 offset:34912
	s_waitcnt lgkmcnt(6)
	v_mfma_f32_32x32x16_bf16 v[76:91], v[116:119], v[120:123], 0
	ds_read_b128 v[116:119], v216 offset:128
	ds_read_b128 v[120:123], v217 offset:34944
	s_waitcnt lgkmcnt(6)
	v_mfma_f32_32x32x16_bf16 v[76:91], v[128:131], v[132:135], v[76:91]
	ds_read_b128 v[128:131], v216 offset:160
	ds_read_b128 v[132:135], v217 offset:34976
	s_waitcnt lgkmcnt(6)
	v_mfma_f32_32x32x16_bf16 v[76:91], v[140:143], v[144:147], v[76:91]
	ds_read_b128 v[140:143], v216 offset:192
	ds_read_b128 v[144:147], v217 offset:35008
	s_waitcnt lgkmcnt(6)
	v_mfma_f32_32x32x16_bf16 v[76:91], v[152:155], v[156:159], v[76:91]
	ds_read_b128 v[152:155], v216 offset:224
	ds_read_b128 v[156:159], v217 offset:35040
	s_waitcnt lgkmcnt(6)
	v_mfma_f32_32x32x16_bf16 v[76:91], v[116:119], v[120:123], v[76:91]
	ds_read_b128 v[234:237], v222 offset:0
	ds_read_b128 v[238:241], v222 offset:32
	ds_read_b128 v[242:245], v222 offset:64
	ds_read_b128 v[246:249], v222 offset:96
	ds_read_b32 v250, v223 offset:0
	s_waitcnt lgkmcnt(9)
	v_mfma_f32_32x32x16_bf16 v[76:91], v[128:131], v[132:135], v[76:91]
	s_waitcnt lgkmcnt(7)
	v_mfma_f32_32x32x16_bf16 v[76:91], v[140:143], v[144:147], v[76:91]
	s_waitcnt lgkmcnt(5)
	v_mfma_f32_32x32x16_bf16 v[76:91], v[152:155], v[156:159], v[76:91]
	s_cmp_lt_u32 s3, 4
	s_cbranch_scc0 .Lm_w456_14
	ds_read_b128 v[176:179], v173 offset:0
	ds_read_b128 v[180:183], v173 offset:32
	ds_read_b128 v[184:187], v173 offset:64
	ds_read_b128 v[188:191], v173 offset:96
	ds_read_b128 v[192:195], v173 offset:128
	ds_read_b128 v[196:199], v173 offset:160
	ds_read_b128 v[200:203], v173 offset:192
	ds_read_b128 v[204:207], v173 offset:224
	ds_read_b32 v2, v211 offset:0
	s_waitcnt lgkmcnt(9)
	v_sub_f32_e32 v116, v234, v250
	v_sub_f32_e32 v117, v235, v250
	v_sub_f32_e32 v118, v236, v250
	v_sub_f32_e32 v119, v237, v250
	v_sub_f32_e32 v120, v238, v250
	v_sub_f32_e32 v121, v239, v250
	v_sub_f32_e32 v122, v240, v250
	v_sub_f32_e32 v123, v241, v250
	v_sub_f32_e32 v124, v242, v250
	v_sub_f32_e32 v125, v243, v250
	v_sub_f32_e32 v126, v244, v250
	v_sub_f32_e32 v127, v245, v250
	v_sub_f32_e32 v128, v246, v250
	v_sub_f32_e32 v129, v247, v250
	v_sub_f32_e32 v130, v248, v250
	v_sub_f32_e32 v131, v249, v250
	v_exp_f32_e32 v116, v116
	v_exp_f32_e32 v117, v117
	v_exp_f32_e32 v118, v118
	v_exp_f32_e32 v119, v119
	v_exp_f32_e32 v120, v120
	v_exp_f32_e32 v121, v121
	v_exp_f32_e32 v122, v122
	v_exp_f32_e32 v123, v123
	v_exp_f32_e32 v124, v124
	v_exp_f32_e32 v125, v125
	v_exp_f32_e32 v126, v126
	v_exp_f32_e32 v127, v127
	v_exp_f32_e32 v128, v128
	v_exp_f32_e32 v129, v129
	v_exp_f32_e32 v130, v130
	v_exp_f32_e32 v131, v131
	v_mul_f32_e32 v76, v76, v116
	v_mul_f32_e32 v77, v77, v117
	v_mul_f32_e32 v78, v78, v118
	v_mul_f32_e32 v79, v79, v119
	v_mul_f32_e32 v80, v80, v120
	v_mul_f32_e32 v81, v81, v121
	v_mul_f32_e32 v82, v82, v122
	v_mul_f32_e32 v83, v83, v123
	v_mul_f32_e32 v84, v84, v124
	v_mul_f32_e32 v85, v85, v125
	v_mul_f32_e32 v86, v86, v126
	v_mul_f32_e32 v87, v87, v127
	v_mul_f32_e32 v88, v88, v128
	v_mul_f32_e32 v89, v89, v129
	v_mul_f32_e32 v90, v90, v130
	v_mul_f32_e32 v91, v91, v131
	s_cmp_eq_u32 s53, 0
	s_cbranch_scc1 .Lm_nodiag_15
	v_cndmask_b32_e64 v76, 0, v76, s[64:65]
	v_cndmask_b32_e64 v77, 0, v77, s[66:67]
	v_cndmask_b32_e64 v78, 0, v78, s[68:69]
	v_cndmask_b32_e64 v79, 0, v79, s[70:71]
	v_cndmask_b32_e64 v80, 0, v80, s[72:73]
	v_cndmask_b32_e64 v81, 0, v81, s[74:75]
	v_cndmask_b32_e64 v82, 0, v82, s[76:77]
	v_cndmask_b32_e64 v83, 0, v83, s[78:79]
	v_cndmask_b32_e64 v84, 0, v84, s[80:81]
	v_cndmask_b32_e64 v85, 0, v85, s[82:83]
	v_cndmask_b32_e64 v86, 0, v86, s[84:85]
	v_cndmask_b32_e64 v87, 0, v87, s[86:87]
	v_cndmask_b32_e64 v88, 0, v88, s[88:89]
	v_cndmask_b32_e64 v89, 0, v89, s[90:91]
	v_cndmask_b32_e64 v90, 0, v90, s[92:93]
	v_cndmask_b32_e64 v91, 0, v91, s[94:95]
.Lm_nodiag_15:
	v_cvt_pk_bf16_f32 v132, v76, v77
	v_cvt_pk_bf16_f32 v133, v78, v79
	v_cvt_pk_bf16_f32 v134, v80, v81
	v_cvt_pk_bf16_f32 v135, v82, v83
	v_cvt_pk_bf16_f32 v136, v84, v85
	v_cvt_pk_bf16_f32 v137, v86, v87
	v_cvt_pk_bf16_f32 v138, v88, v89
	v_cvt_pk_bf16_f32 v139, v90, v91
	ds_write_b64 v224, v[132:133] offset:0
	ds_write_b64 v224, v[134:135] offset:16
	ds_write_b64 v224, v[136:137] offset:32
	ds_write_b64 v224, v[138:139] offset:48
	s_branch .Lm_adone_11
.Lm_w456_14:
	s_waitcnt lgkmcnt(0)
	ds_read_b32 v1, v172 offset:0
	ds_read_b64_tr_b16 v[116:117], v193 offset:0
	ds_read_b64_tr_b16 v[118:119], v193 offset:1088
	ds_read_b64_tr_b16 v[120:121], v192 offset:0
	ds_read_b64_tr_b16 v[122:123], v192 offset:320
	ds_read_b64_tr_b16 v[124:125], v193 offset:4352
	ds_read_b64_tr_b16 v[126:127], v193 offset:5440
	ds_read_b64_tr_b16 v[128:129], v192 offset:1280
	ds_read_b64_tr_b16 v[130:131], v192 offset:1600
	ds_read_b64_tr_b16 v[132:133], v193 offset:8704
	ds_read_b64_tr_b16 v[134:135], v193 offset:9792
	ds_read_b64_tr_b16 v[136:137], v192 offset:2560
	ds_read_b64_tr_b16 v[138:139], v192 offset:2880
	s_waitcnt lgkmcnt(12)
	v_exp_f32_e32 v1, v1
	s_nop 0
	v_mul_f32_e32 v176, v176, v1
	v_mul_f32_e32 v177, v177, v1
	v_mul_f32_e32 v178, v178, v1
	v_mul_f32_e32 v179, v179, v1
	v_mul_f32_e32 v180, v180, v1
	v_mul_f32_e32 v181, v181, v1
	v_mul_f32_e32 v182, v182, v1
	v_mul_f32_e32 v183, v183, v1
	v_mul_f32_e32 v184, v184, v1
	v_mul_f32_e32 v185, v185, v1
	v_mul_f32_e32 v186, v186, v1
	v_mul_f32_e32 v187, v187, v1
	v_mul_f32_e32 v188, v188, v1
	v_mul_f32_e32 v189, v189, v1
	v_mul_f32_e32 v190, v190, v1
	v_mul_f32_e32 v191, v191, v1
	s_nop 1
	s_waitcnt lgkmcnt(8)
	v_mfma_f32_32x32x16_bf16 v[176:191], v[116:119], v[120:123], v[176:191]
	ds_read_b64_tr_b16 v[116:117], v193 offset:13056
	ds_read_b64_tr_b16 v[118:119], v193 offset:14144
	ds_read_b64_tr_b16 v[120:121], v192 offset:3840
	ds_read_b64_tr_b16 v[122:123], v192 offset:4160
	s_waitcnt lgkmcnt(8)
	v_mfma_f32_32x32x16_bf16 v[176:191], v[124:127], v[128:131], v[176:191]
	ds_read_b64_tr_b16 v[124:125], v193 offset:17408
	ds_read_b64_tr_b16 v[126:127], v193 offset:18496
	ds_read_b64_tr_b16 v[128:129], v192 offset:5120
	ds_read_b64_tr_b16 v[130:131], v192 offset:5440
	s_waitcnt lgkmcnt(8)
	v_mfma_f32_32x32x16_bf16 v[176:191], v[132:135], v[136:139], v[176:191]
	ds_read_b64_tr_b16 v[132:133], v193 offset:21760
	ds_read_b64_tr_b16 v[134:135], v193 offset:22848
	ds_read_b64_tr_b16 v[136:137], v192 offset:6400
	ds_read_b64_tr_b16 v[138:139], v192 offset:6720
	s_waitcnt lgkmcnt(8)
	v_mfma_f32_32x32x16_bf16 v[176:191], v[116:119], v[120:123], v[176:191]
	ds_read_b64_tr_b16 v[116:117], v193 offset:26112
	ds_read_b64_tr_b16 v[118:119], v193 offset:27200
	ds_read_b64_tr_b16 v[120:121], v192 offset:7680
	ds_read_b64_tr_b16 v[122:123], v192 offset:8000
	s_waitcnt lgkmcnt(8)
	v_mfma_f32_32x32x16_bf16 v[176:191], v[124:127], v[128:131], v[176:191]
	ds_read_b64_tr_b16 v[124:125], v193 offset:30464
	ds_read_b64_tr_b16 v[126:127], v193 offset:31552
	ds_read_b64_tr_b16 v[128:129], v192 offset:8960
	ds_read_b64_tr_b16 v[130:131], v192 offset:9280
	s_waitcnt lgkmcnt(8)
	v_mfma_f32_32x32x16_bf16 v[176:191], v[132:135], v[136:139], v[176:191]
	s_waitcnt lgkmcnt(4)
	v_mfma_f32_32x32x16_bf16 v[176:191], v[116:119], v[120:123], v[176:191]
	s_waitcnt lgkmcnt(0)
	v_mfma_f32_32x32x16_bf16 v[176:191], v[124:127], v[128:131], v[176:191]
	v_sub_f32_e32 v116, v234, v250
	v_sub_f32_e32 v117, v235, v250
	v_sub_f32_e32 v118, v236, v250
	v_sub_f32_e32 v119, v237, v250
	v_sub_f32_e32 v120, v238, v250
	v_sub_f32_e32 v121, v239, v250
	v_sub_f32_e32 v122, v240, v250
	v_sub_f32_e32 v123, v241, v250
	v_sub_f32_e32 v124, v242, v250
	v_sub_f32_e32 v125, v243, v250
	v_sub_f32_e32 v126, v244, v250
	v_sub_f32_e32 v127, v245, v250
	v_sub_f32_e32 v128, v246, v250
	v_sub_f32_e32 v129, v247, v250
	v_sub_f32_e32 v130, v248, v250
	v_sub_f32_e32 v131, v249, v250
	v_exp_f32_e32 v116, v116
	v_exp_f32_e32 v117, v117
	v_exp_f32_e32 v118, v118
	v_exp_f32_e32 v119, v119
	v_exp_f32_e32 v120, v120
	v_exp_f32_e32 v121, v121
	v_exp_f32_e32 v122, v122
	v_exp_f32_e32 v123, v123
	v_exp_f32_e32 v124, v124
	v_exp_f32_e32 v125, v125
	v_exp_f32_e32 v126, v126
	v_exp_f32_e32 v127, v127
	v_exp_f32_e32 v128, v128
	v_exp_f32_e32 v129, v129
	v_exp_f32_e32 v130, v130
	v_exp_f32_e32 v131, v131
	v_mul_f32_e32 v76, v76, v116
	v_mul_f32_e32 v77, v77, v117
	v_mul_f32_e32 v78, v78, v118
	v_mul_f32_e32 v79, v79, v119
	v_mul_f32_e32 v80, v80, v120
	v_mul_f32_e32 v81, v81, v121
	v_mul_f32_e32 v82, v82, v122
	v_mul_f32_e32 v83, v83, v123
	v_mul_f32_e32 v84, v84, v124
	v_mul_f32_e32 v85, v85, v125
	v_mul_f32_e32 v86, v86, v126
	v_mul_f32_e32 v87, v87, v127
	v_mul_f32_e32 v88, v88, v128
	v_mul_f32_e32 v89, v89, v129
	v_mul_f32_e32 v90, v90, v130
	v_mul_f32_e32 v91, v91, v131
	s_cmp_eq_u32 s53, 0
	s_cbranch_scc1 .Lm_nodiag_16
	v_cndmask_b32_e64 v76, 0, v76, s[64:65]
	v_cndmask_b32_e64 v77, 0, v77, s[66:67]
	v_cndmask_b32_e64 v78, 0, v78, s[68:69]
	v_cndmask_b32_e64 v79, 0, v79, s[70:71]
	v_cndmask_b32_e64 v80, 0, v80, s[72:73]
	v_cndmask_b32_e64 v81, 0, v81, s[74:75]
	v_cndmask_b32_e64 v82, 0, v82, s[76:77]
	v_cndmask_b32_e64 v83, 0, v83, s[78:79]
	v_cndmask_b32_e64 v84, 0, v84, s[80:81]
	v_cndmask_b32_e64 v85, 0, v85, s[82:83]
	v_cndmask_b32_e64 v86, 0, v86, s[84:85]
	v_cndmask_b32_e64 v87, 0, v87, s[86:87]
	v_cndmask_b32_e64 v88, 0, v88, s[88:89]
	v_cndmask_b32_e64 v89, 0, v89, s[90:91]
	v_cndmask_b32_e64 v90, 0, v90, s[92:93]
	v_cndmask_b32_e64 v91, 0, v91, s[94:95]
.Lm_nodiag_16:
	v_cvt_pk_bf16_f32 v132, v76, v77
	v_cvt_pk_bf16_f32 v133, v78, v79
	v_cvt_pk_bf16_f32 v134, v80, v81
	v_cvt_pk_bf16_f32 v135, v82, v83
	v_cvt_pk_bf16_f32 v136, v84, v85
	v_cvt_pk_bf16_f32 v137, v86, v87
	v_cvt_pk_bf16_f32 v138, v88, v89
	v_cvt_pk_bf16_f32 v139, v90, v91
	ds_write_b64 v224, v[132:133] offset:0
	ds_write_b64 v224, v[134:135] offset:16
	ds_write_b64 v224, v[136:137] offset:32
	ds_write_b64 v224, v[138:139] offset:48
	v_cvt_pk_bf16_f32 v140, v176, v177
	v_cvt_pk_bf16_f32 v141, v178, v179
	v_cvt_pk_bf16_f32 v142, v180, v181
	v_cvt_pk_bf16_f32 v143, v182, v183
	v_cvt_pk_bf16_f32 v144, v184, v185
	v_cvt_pk_bf16_f32 v145, v186, v187
	v_cvt_pk_bf16_f32 v146, v188, v189
	v_cvt_pk_bf16_f32 v147, v190, v191
	ds_write_b64 v194, v[140:141] offset:8704
	ds_write_b64 v194, v[142:143] offset:8720
	ds_write_b64 v194, v[144:145] offset:8736
	ds_write_b64 v194, v[146:147] offset:8752
	s_branch .Lm_adone_11
.Lm_g0_8:
	ds_read_b32 v1, v172 offset:0
	ds_read_b64_tr_b16 v[116:117], v193 offset:0
	ds_read_b64_tr_b16 v[118:119], v193 offset:1088
	ds_read_b64_tr_b16 v[120:121], v192 offset:0
	ds_read_b64_tr_b16 v[122:123], v192 offset:320
	ds_read_b64_tr_b16 v[124:125], v193 offset:4352
	ds_read_b64_tr_b16 v[126:127], v193 offset:5440
	ds_read_b64_tr_b16 v[128:129], v192 offset:1280
	ds_read_b64_tr_b16 v[130:131], v192 offset:1600
	ds_read_b64_tr_b16 v[132:133], v193 offset:8704
	ds_read_b64_tr_b16 v[134:135], v193 offset:9792
	ds_read_b64_tr_b16 v[136:137], v192 offset:2560
	ds_read_b64_tr_b16 v[138:139], v192 offset:2880
	s_waitcnt lgkmcnt(12)
	v_exp_f32_e32 v1, v1
	s_nop 0
	v_mul_f32_e32 v176, v176, v1
	v_mul_f32_e32 v177, v177, v1
	v_mul_f32_e32 v178, v178, v1
	v_mul_f32_e32 v179, v179, v1
	v_mul_f32_e32 v180, v180, v1
	v_mul_f32_e32 v181, v181, v1
	v_mul_f32_e32 v182, v182, v1
	v_mul_f32_e32 v183, v183, v1
	v_mul_f32_e32 v184, v184, v1
	v_mul_f32_e32 v185, v185, v1
	v_mul_f32_e32 v186, v186, v1
	v_mul_f32_e32 v187, v187, v1
	v_mul_f32_e32 v188, v188, v1
	v_mul_f32_e32 v189, v189, v1
	v_mul_f32_e32 v190, v190, v1
	v_mul_f32_e32 v191, v191, v1
	s_nop 1
	s_waitcnt lgkmcnt(8)
	v_mfma_f32_32x32x16_bf16 v[176:191], v[116:119], v[120:123], v[176:191]
	ds_read_b64_tr_b16 v[116:117], v193 offset:13056
	ds_read_b64_tr_b16 v[118:119], v193 offset:14144
	ds_read_b64_tr_b16 v[120:121], v192 offset:3840
	ds_read_b64_tr_b16 v[122:123], v192 offset:4160
	s_waitcnt lgkmcnt(8)
	v_mfma_f32_32x32x16_bf16 v[176:191], v[124:127], v[128:131], v[176:191]
	ds_read_b64_tr_b16 v[124:125], v193 offset:17408
	ds_read_b64_tr_b16 v[126:127], v193 offset:18496
	ds_read_b64_tr_b16 v[128:129], v192 offset:5120
	ds_read_b64_tr_b16 v[130:131], v192 offset:5440
	s_waitcnt lgkmcnt(8)
	v_mfma_f32_32x32x16_bf16 v[176:191], v[132:135], v[136:139], v[176:191]
	ds_read_b64_tr_b16 v[132:133], v193 offset:21760
	ds_read_b64_tr_b16 v[134:135], v193 offset:22848
	ds_read_b64_tr_b16 v[136:137], v192 offset:6400
	ds_read_b64_tr_b16 v[138:139], v192 offset:6720
	s_waitcnt lgkmcnt(8)
	v_mfma_f32_32x32x16_bf16 v[176:191], v[116:119], v[120:123], v[176:191]
	ds_read_b64_tr_b16 v[116:117], v193 offset:26112
	ds_read_b64_tr_b16 v[118:119], v193 offset:27200
	ds_read_b64_tr_b16 v[120:121], v192 offset:7680
	ds_read_b64_tr_b16 v[122:123], v192 offset:8000
	s_waitcnt lgkmcnt(8)
	v_mfma_f32_32x32x16_bf16 v[176:191], v[124:127], v[128:131], v[176:191]
	ds_read_b64_tr_b16 v[124:125], v193 offset:30464
	ds_read_b64_tr_b16 v[126:127], v193 offset:31552
	ds_read_b64_tr_b16 v[128:129], v192 offset:8960
	ds_read_b64_tr_b16 v[130:131], v192 offset:9280
	s_waitcnt lgkmcnt(8)
	v_mfma_f32_32x32x16_bf16 v[176:191], v[132:135], v[136:139], v[176:191]
	s_waitcnt lgkmcnt(4)
	v_mfma_f32_32x32x16_bf16 v[176:191], v[116:119], v[120:123], v[176:191]
	s_waitcnt lgkmcnt(0)
	v_mfma_f32_32x32x16_bf16 v[176:191], v[124:127], v[128:131], v[176:191]
	s_nop 7
	s_nop 3
	v_cvt_pk_bf16_f32 v140, v176, v177
	v_cvt_pk_bf16_f32 v141, v178, v179
	v_cvt_pk_bf16_f32 v142, v180, v181
	v_cvt_pk_bf16_f32 v143, v182, v183
	v_cvt_pk_bf16_f32 v144, v184, v185
	v_cvt_pk_bf16_f32 v145, v186, v187
	v_cvt_pk_bf16_f32 v146, v188, v189
	v_cvt_pk_bf16_f32 v147, v190, v191
	ds_write_b64 v194, v[140:141] offset:8704
	ds_write_b64 v194, v[142:143] offset:8720
	ds_write_b64 v194, v[144:145] offset:8736
	ds_write_b64 v194, v[146:147] offset:8752
	s_cmp_lt_u32 s50, 63
	s_cbranch_scc0 .Lm_noscan_17
	s_cmp_lt_u32 s50, 62
	s_cbranch_scc0 .Lm_sc0_18
	s_waitcnt vmcnt(9)
	s_branch .Lm_scgo_19

.Lm_scgo_19:
	s_waitcnt lgkmcnt(0)
	v_mul_f32_e32 v116, s62, v204
	v_mul_f32_e32 v117, s62, v205
	v_add_f32_e32 v118, v116, v117
	ds_bpermute_b32 v119, v197, v118
	s_waitcnt lgkmcnt(0)
	v_add_f32_e32 v119, v118, v119
	v_cndmask_b32_e64 v118, v118, v119, s[16:17]
	ds_bpermute_b32 v119, v198, v118
	s_waitcnt lgkmcnt(0)
	v_add_f32_e32 v119, v118, v119
	v_cndmask_b32_e64 v118, v118, v119, s[18:19]
	ds_bpermute_b32 v119, v199, v118
	s_waitcnt lgkmcnt(0)
	v_add_f32_e32 v119, v118, v119
	v_cndmask_b32_e64 v118, v118, v119, s[20:21]
	ds_bpermute_b32 v119, v200, v118
	s_waitcnt lgkmcnt(0)
	v_add_f32_e32 v119, v118, v119
	v_cndmask_b32_e64 v118, v118, v119, s[22:23]
	ds_bpermute_b32 v119, v201, v118
	s_waitcnt lgkmcnt(0)
	v_add_f32_e32 v119, v118, v119
	v_cndmask_b32_e64 v118, v118, v119, s[24:25]
	ds_bpermute_b32 v119, v202, v118
	s_waitcnt lgkmcnt(0)
	v_add_f32_e32 v119, v118, v119
	v_cndmask_b32_e64 v118, v118, v119, s[26:27]
	ds_bpermute_b32 v120, v225, v118
	v_sub_f32_e32 v122, v118, v117
	v_mov_b32_e32 v123, v118
	s_waitcnt lgkmcnt(0)
	s_cmp_eq_u32 s51, 0
	s_cbranch_scc1 .Lm_scanf_20
	v_sub_f32_e32 v122, v120, v122
	v_sub_f32_e32 v123, v120, v123
	v_fma_f32 v122, v204, s62, v122
	v_fma_f32 v123, v205, s62, v123
.Lm_scanf_20:
	v_mul_f32_e32 v122, 0x3fb8aa3b, v122
	v_mul_f32_e32 v123, 0x3fb8aa3b, v123
	v_mul_f32_e32 v120, 0x3fb8aa3b, v120
	ds_write_b64 v196, v[122:123] offset:2048
	ds_write_b64 v196, v[204:205] offset:2560
	ds_write_b32 v172, v120 offset:2048
	s_cmp_lt_u32 s50, 62
	s_cbranch_scc0 .Lm_noscan_17
	s_waitcnt lgkmcnt(0)
	global_load_dword v204, v195, s[42:43]
	global_load_dword v205, v195, s[42:43] offset:256
	s_add_u32 s42, s42, s48
	s_addc_u32 s43, s43, s55
.Lm_noscan_17:
.Lm_adone_11:
	s_waitcnt lgkmcnt(0)
	s_barrier
	s_cmp_lt_u32 s3, 4
	s_cbranch_scc0 .Lm_noy_21
	ds_read_b64_tr_b16 v[116:117], v208 offset:0
	ds_read_b64_tr_b16 v[118:119], v208 offset:320
	ds_read_b64_tr_b16 v[120:121], v209 offset:0
	ds_read_b64_tr_b16 v[122:123], v209 offset:1088
	ds_read_b128 v[124:127], v210 offset:0
	ds_read_b64_tr_b16 v[128:129], v208 offset:1280
	ds_read_b64_tr_b16 v[130:131], v208 offset:1600
	ds_read_b64_tr_b16 v[132:133], v209 offset:4352
	ds_read_b64_tr_b16 v[134:135], v209 offset:5440
	ds_read_b128 v[136:139], v210 offset:32
	ds_read_b64_tr_b16 v[140:141], v208 offset:2560
	ds_read_b64_tr_b16 v[142:143], v208 offset:2880
	ds_read_b64_tr_b16 v[144:145], v209 offset:8704
	ds_read_b64_tr_b16 v[146:147], v209 offset:9792
	ds_read_b128 v[148:151], v210 offset:64
	s_waitcnt lgkmcnt(10)
	v_mfma_f32_32x32x16_bf16 v[76:91], v[116:119], v[120:123], 0
	v_mfma_f32_32x32x16_bf16 v[92:107], v[124:127], v[176:179], 0
	ds_read_b64_tr_b16 v[116:117], v208 offset:3840
	ds_read_b64_tr_b16 v[118:119], v208 offset:4160
	ds_read_b64_tr_b16 v[120:121], v209 offset:13056
	ds_read_b64_tr_b16 v[122:123], v209 offset:14144
	ds_read_b128 v[124:127], v210 offset:96
	s_waitcnt lgkmcnt(10)
	v_mfma_f32_32x32x16_bf16 v[76:91], v[128:131], v[132:135], v[76:91]
	v_mfma_f32_32x32x16_bf16 v[92:107], v[136:139], v[180:183], v[92:107]
	ds_read_b64_tr_b16 v[128:129], v208 offset:5120
	ds_read_b64_tr_b16 v[130:131], v208 offset:5440
	ds_read_b64_tr_b16 v[132:133], v209 offset:17408
	ds_read_b64_tr_b16 v[134:135], v209 offset:18496
	ds_read_b128 v[136:139], v210 offset:128
	s_waitcnt lgkmcnt(10)
	v_mfma_f32_32x32x16_bf16 v[76:91], v[140:143], v[144:147], v[76:91]
	v_mfma_f32_32x32x16_bf16 v[92:107], v[148:151], v[184:187], v[92:107]
	ds_read_b64_tr_b16 v[140:141], v208 offset:6400
	ds_read_b64_tr_b16 v[142:143], v208 offset:6720
	ds_read_b64_tr_b16 v[144:145], v209 offset:21760
	ds_read_b64_tr_b16 v[146:147], v209 offset:22848
	ds_read_b128 v[148:151], v210 offset:160
	s_waitcnt lgkmcnt(10)
	v_mfma_f32_32x32x16_bf16 v[76:91], v[116:119], v[120:123], v[76:91]
	v_mfma_f32_32x32x16_bf16 v[92:107], v[124:127], v[188:191], v[92:107]
	ds_read_b64_tr_b16 v[116:117], v208 offset:7680
	ds_read_b64_tr_b16 v[118:119], v208 offset:8000
	ds_read_b64_tr_b16 v[120:121], v209 offset:26112
	ds_read_b64_tr_b16 v[122:123], v209 offset:27200
	ds_read_b128 v[124:127], v210 offset:192
	s_waitcnt lgkmcnt(10)
	v_mfma_f32_32x32x16_bf16 v[76:91], v[128:131], v[132:135], v[76:91]
	v_mfma_f32_32x32x16_bf16 v[92:107], v[136:139], v[192:195], v[92:107]
	ds_read_b64_tr_b16 v[128:129], v208 offset:8960
	ds_read_b64_tr_b16 v[130:131], v208 offset:9280
	ds_read_b64_tr_b16 v[132:133], v209 offset:30464
	ds_read_b64_tr_b16 v[134:135], v209 offset:31552
	ds_read_b128 v[136:139], v210 offset:224
	s_waitcnt lgkmcnt(10)
	v_mfma_f32_32x32x16_bf16 v[76:91], v[140:143], v[144:147], v[76:91]
	v_mfma_f32_32x32x16_bf16 v[92:107], v[148:151], v[196:199], v[92:107]
	s_waitcnt lgkmcnt(5)
	v_mfma_f32_32x32x16_bf16 v[76:91], v[116:119], v[120:123], v[76:91]
	v_mfma_f32_32x32x16_bf16 v[92:107], v[124:127], v[200:203], v[92:107]
	s_waitcnt lgkmcnt(0)
	v_mfma_f32_32x32x16_bf16 v[76:91], v[128:131], v[132:135], v[76:91]
	v_mfma_f32_32x32x16_bf16 v[92:107], v[136:139], v[204:207], v[92:107]
.Lm_noy_21:
	s_cmp_lt_u32 s50, 63
	s_cbranch_scc0 .Lm_now_22
	s_cmp_lt_u32 s50, 62
	s_cbranch_scc0 .Lm_w0_23
	s_waitcnt vmcnt(9)
	s_branch .Lm_wgo_24

.Lm_wgo_24:
	ds_read_b32 v116, v172 offset:2048
	ds_read_b32 v117, v171 offset:2048
	ds_read_b32 v118, v171 offset:2560
	ds_write_b128 v169, v[56:59] offset:0
	ds_write_b128 v169, v[40:43] offset:34816
	ds_write_b128 v169, v[60:63] offset:8704
	ds_write_b128 v169, v[44:47] offset:43520
	ds_write_b128 v169, v[64:67] offset:17408
	ds_write_b128 v169, v[48:51] offset:52224
	ds_write_b128 v169, v[68:71] offset:26112
	ds_write_b128 v169, v[52:55] offset:60928
	v_lshlrev_b32_e32 v120, 16, v72
	v_and_b32_e32 v121, 0xffff0000, v72
	v_lshlrev_b32_e32 v122, 16, v73
	v_and_b32_e32 v123, 0xffff0000, v73
	v_lshlrev_b32_e32 v124, 16, v74
	v_and_b32_e32 v125, 0xffff0000, v74
	v_lshlrev_b32_e32 v126, 16, v75
	v_and_b32_e32 v127, 0xffff0000, v75
	s_waitcnt lgkmcnt(8)
	v_sub_f32_e32 v119, v116, v117
	v_exp_f32_e32 v119, v119
	v_mul_f32_e32 v128, v118, v120
	v_mul_f32_e32 v129, v118, v121
	v_mul_f32_e32 v130, v118, v122
	v_mul_f32_e32 v131, v118, v123
	v_mul_f32_e32 v132, v118, v124
	v_mul_f32_e32 v133, v118, v125
	v_mul_f32_e32 v134, v118, v126
	v_mul_f32_e32 v135, v118, v127
	v_mul_f32_e32 v119, v118, v119
	v_cvt_pk_bf16_f32 v144, v128, v129
	v_cvt_pk_bf16_f32 v145, v130, v131
	v_cvt_pk_bf16_f32 v146, v132, v133
	v_cvt_pk_bf16_f32 v147, v134, v135
	v_mul_f32_e32 v136, v119, v120
	v_mul_f32_e32 v137, v119, v121
	v_mul_f32_e32 v138, v119, v122
	v_mul_f32_e32 v139, v119, v123
	v_mul_f32_e32 v140, v119, v124
	v_mul_f32_e32 v141, v119, v125
	v_mul_f32_e32 v142, v119, v126
	v_mul_f32_e32 v143, v119, v127
	v_cvt_pk_bf16_f32 v148, v136, v137
	v_cvt_pk_bf16_f32 v149, v138, v139
	v_cvt_pk_bf16_f32 v150, v140, v141
	v_cvt_pk_bf16_f32 v151, v142, v143
	ds_write_b128 v170, v[144:147] offset:43008
	ds_write_b128 v170, v[148:151] offset:10240
.Lm_now_22:
	s_nop 7
	s_nop 3
	s_cmp_lt_u32 s3, 4
	s_cbranch_scc0 .Lm_noy2_25
	v_exp_f32_e32 v2, v2
	s_nop 0
	v_fma_f32 v76, v92, v2, v76
	v_fma_f32 v77, v93, v2, v77
	v_fma_f32 v78, v94, v2, v78
	v_fma_f32 v79, v95, v2, v79
	v_fma_f32 v80, v96, v2, v80
	v_fma_f32 v81, v97, v2, v81
	v_fma_f32 v82, v98, v2, v82
	v_fma_f32 v83, v99, v2, v83
	v_fma_f32 v84, v100, v2, v84
	v_fma_f32 v85, v101, v2, v85
	v_fma_f32 v86, v102, v2, v86
	v_fma_f32 v87, v103, v2, v87
	v_fma_f32 v88, v104, v2, v88
	v_fma_f32 v89, v105, v2, v89
	v_fma_f32 v90, v106, v2, v90
	v_fma_f32 v91, v107, v2, v91
	v_cvt_pk_bf16_f32 v156, v76, v77
	v_cvt_pk_bf16_f32 v157, v78, v79
	v_cvt_pk_bf16_f32 v158, v80, v81
	v_cvt_pk_bf16_f32 v159, v82, v83
	v_cvt_pk_bf16_f32 v160, v84, v85
	v_cvt_pk_bf16_f32 v161, v86, v87
	v_cvt_pk_bf16_f32 v162, v88, v89
	v_cvt_pk_bf16_f32 v163, v90, v91
	global_store_dwordx2 v212, v[156:157], s[44:45] offset:0
	global_store_dwordx2 v212, v[158:159], s[44:45] offset:16
	global_store_dwordx2 v212, v[160:161], s[44:45] offset:32
	global_store_dwordx2 v212, v[162:163], s[44:45] offset:48
.Lm_noy2_25:
	s_add_u32 s44, s44, s49
	s_addc_u32 s45, s45, s55
	s_waitcnt lgkmcnt(0)
	s_cmp_lt_u32 s50, 61
	s_cbranch_scc0 .Lm_nold_26
	global_load_dwordx4 v[40:43], v164, s[38:39]
	global_load_dwordx4 v[56:59], v164, s[38:39] offset:256
	global_load_dwordx4 v[44:47], v165, s[38:39]
	global_load_dwordx4 v[60:63], v165, s[38:39] offset:256
	global_load_dwordx4 v[48:51], v166, s[38:39]
	global_load_dwordx4 v[64:67], v166, s[38:39] offset:256
	global_load_dwordx4 v[52:55], v167, s[38:39]
	global_load_dwordx4 v[68:71], v167, s[38:39] offset:256
	global_load_dwordx4 v[72:75], v168, s[40:41]
	s_add_u32 s38, s38, s46
	s_addc_u32 s39, s39, s55
	s_add_u32 s40, s40, s47
	s_addc_u32 s41, s41, s55
.Lm_nold_26:
	s_barrier
	s_add_u32 s50, s50, 1
	s_cmp_eq_u32 s52, 2
	s_cbranch_scc0 .Lm_g1_27
	ds_read_b128 v[116:119], v216 offset:0
	ds_read_b128 v[120:123], v217 offset:34816
	ds_read_b128 v[124:127], v217 offset:43520
	ds_read_b128 v[128:131], v216 offset:32
	ds_read_b128 v[132:135], v217 offset:34848
	ds_read_b128 v[136:139], v217 offset:43552
	ds_read_b128 v[140:143], v216 offset:64
	ds_read_b128 v[144:147], v217 offset:34880
	ds_read_b128 v[148:151], v217 offset:43584
	ds_read_b128 v[152:155], v216 offset:96
	ds_read_b128 v[156:159], v217 offset:34912
	ds_read_b128 v[160:163], v217 offset:43616
	s_waitcnt lgkmcnt(9)
	v_mfma_f32_32x32x16_bf16 v[76:91], v[116:119], v[120:123], 0
	v_mfma_f32_32x32x16_bf16 v[92:107], v[116:119], v[124:127], 0
	ds_read_b128 v[116:119], v216 offset:128
	ds_read_b128 v[120:123], v217 offset:34944
	ds_read_b128 v[124:127], v217 offset:43648
	s_waitcnt lgkmcnt(9)
	v_mfma_f32_32x32x16_bf16 v[76:91], v[128:131], v[132:135], v[76:91]
	v_mfma_f32_32x32x16_bf16 v[92:107], v[128:131], v[136:139], v[92:107]
	ds_read_b128 v[128:131], v216 offset:160
	ds_read_b128 v[132:135], v217 offset:34976
	ds_read_b128 v[136:139], v217 offset:43680
	s_waitcnt lgkmcnt(9)
	v_mfma_f32_32x32x16_bf16 v[76:91], v[140:143], v[144:147], v[76:91]
	v_mfma_f32_32x32x16_bf16 v[92:107], v[140:143], v[148:151], v[92:107]
	ds_read_b128 v[140:143], v216 offset:192
	ds_read_b128 v[144:147], v217 offset:35008
	ds_read_b128 v[148:151], v217 offset:43712
	s_waitcnt lgkmcnt(9)
	v_mfma_f32_32x32x16_bf16 v[76:91], v[152:155], v[156:159], v[76:91]
	v_mfma_f32_32x32x16_bf16 v[92:107], v[152:155], v[160:163], v[92:107]
	ds_read_b128 v[152:155], v216 offset:224
	ds_read_b128 v[156:159], v217 offset:35040
	ds_read_b128 v[160:163], v217 offset:43744
	s_waitcnt lgkmcnt(9)
	v_mfma_f32_32x32x16_bf16 v[76:91], v[116:119], v[120:123], v[76:91]
	v_mfma_f32_32x32x16_bf16 v[92:107], v[116:119], v[124:127], v[92:107]
	ds_read_b128 v[234:237], v222 offset:2048
	ds_read_b128 v[238:241], v222 offset:2080
	ds_read_b128 v[242:245], v222 offset:2112
	ds_read_b128 v[246:249], v222 offset:2144
	ds_read_b32 v250, v223 offset:2048
	ds_read_b32 v251, v223 offset:2176
	s_waitcnt lgkmcnt(12)
	v_mfma_f32_32x32x16_bf16 v[76:91], v[128:131], v[132:135], v[76:91]
	v_mfma_f32_32x32x16_bf16 v[92:107], v[128:131], v[136:139], v[92:107]
	s_waitcnt lgkmcnt(9)
	v_mfma_f32_32x32x16_bf16 v[76:91], v[140:143], v[144:147], v[76:91]
	v_mfma_f32_32x32x16_bf16 v[92:107], v[140:143], v[148:151], v[92:107]
	s_waitcnt lgkmcnt(6)
	v_mfma_f32_32x32x16_bf16 v[76:91], v[152:155], v[156:159], v[76:91]
	v_mfma_f32_32x32x16_bf16 v[92:107], v[152:155], v[160:163], v[92:107]
	ds_read_b128 v[176:179], v173 offset:0
	ds_read_b128 v[180:183], v173 offset:32
	ds_read_b128 v[184:187], v173 offset:64
	ds_read_b128 v[188:191], v173 offset:96
	ds_read_b128 v[192:195], v173 offset:128
	ds_read_b128 v[196:199], v173 offset:160
	ds_read_b128 v[200:203], v173 offset:192
	ds_read_b128 v[204:207], v173 offset:224
	ds_read_b32 v2, v211 offset:2048
	s_waitcnt lgkmcnt(9)
	v_sub_f32_e32 v116, v234, v250
	v_sub_f32_e32 v117, v235, v250
	v_sub_f32_e32 v118, v236, v250
	v_sub_f32_e32 v119, v237, v250
	v_sub_f32_e32 v120, v238, v250
	v_sub_f32_e32 v121, v239, v250
	v_sub_f32_e32 v122, v240, v250
	v_sub_f32_e32 v123, v241, v250
	v_sub_f32_e32 v124, v242, v250
	v_sub_f32_e32 v125, v243, v250
	v_sub_f32_e32 v126, v244, v250
	v_sub_f32_e32 v127, v245, v250
	v_sub_f32_e32 v128, v246, v250
	v_sub_f32_e32 v129, v247, v250
	v_sub_f32_e32 v130, v248, v250
	v_sub_f32_e32 v131, v249, v250
	v_exp_f32_e32 v116, v116
	v_exp_f32_e32 v117, v117
	v_exp_f32_e32 v118, v118
	v_exp_f32_e32 v119, v119
	v_exp_f32_e32 v120, v120
	v_exp_f32_e32 v121, v121
	v_exp_f32_e32 v122, v122
	v_exp_f32_e32 v123, v123
	v_exp_f32_e32 v124, v124
	v_exp_f32_e32 v125, v125
	v_exp_f32_e32 v126, v126
	v_exp_f32_e32 v127, v127
	v_exp_f32_e32 v128, v128
	v_exp_f32_e32 v129, v129
	v_exp_f32_e32 v130, v130
	v_exp_f32_e32 v131, v131
	v_mul_f32_e32 v76, v76, v116
	v_mul_f32_e32 v77, v77, v117
	v_mul_f32_e32 v78, v78, v118
	v_mul_f32_e32 v79, v79, v119
	v_mul_f32_e32 v80, v80, v120
	v_mul_f32_e32 v81, v81, v121
	v_mul_f32_e32 v82, v82, v122
	v_mul_f32_e32 v83, v83, v123
	v_mul_f32_e32 v84, v84, v124
	v_mul_f32_e32 v85, v85, v125
	v_mul_f32_e32 v86, v86, v126
	v_mul_f32_e32 v87, v87, v127
	v_mul_f32_e32 v88, v88, v128
	v_mul_f32_e32 v89, v89, v129
	v_mul_f32_e32 v90, v90, v130
	v_mul_f32_e32 v91, v91, v131
	s_cmp_eq_u32 s53, 0
	s_cbranch_scc1 .Lm_nodiag_32
	v_cndmask_b32_e64 v76, 0, v76, s[64:65]
	v_cndmask_b32_e64 v77, 0, v77, s[66:67]
	v_cndmask_b32_e64 v78, 0, v78, s[68:69]
	v_cndmask_b32_e64 v79, 0, v79, s[70:71]
	v_cndmask_b32_e64 v80, 0, v80, s[72:73]
	v_cndmask_b32_e64 v81, 0, v81, s[74:75]
	v_cndmask_b32_e64 v82, 0, v82, s[76:77]
	v_cndmask_b32_e64 v83, 0, v83, s[78:79]
	v_cndmask_b32_e64 v84, 0, v84, s[80:81]
	v_cndmask_b32_e64 v85, 0, v85, s[82:83]
	v_cndmask_b32_e64 v86, 0, v86, s[84:85]
	v_cndmask_b32_e64 v87, 0, v87, s[86:87]
	v_cndmask_b32_e64 v88, 0, v88, s[88:89]
	v_cndmask_b32_e64 v89, 0, v89, s[90:91]
	v_cndmask_b32_e64 v90, 0, v90, s[92:93]
	v_cndmask_b32_e64 v91, 0, v91, s[94:95]

.Lm_g1_27:
	s_cmp_eq_u32 s52, 1
	s_cbranch_scc0 .Lm_g0_28
	ds_read_b128 v[116:119], v216 offset:0
	ds_read_b128 v[120:123], v217 offset:34816
	ds_read_b128 v[128:131], v216 offset:32
	ds_read_b128 v[132:135], v217 offset:34848
	ds_read_b128 v[140:143], v216 offset:64
	ds_read_b128 v[144:147], v217 offset:34880
	ds_read_b128 v[152:155], v216 offset:96
	ds_read_b128 v[156:159], v217 offset:34912
	s_waitcnt lgkmcnt(6)
	v_mfma_f32_32x32x16_bf16 v[76:91], v[116:119], v[120:123], 0
	ds_read_b128 v[116:119], v216 offset:128
	ds_read_b128 v[120:123], v217 offset:34944
	s_waitcnt lgkmcnt(6)
	v_mfma_f32_32x32x16_bf16 v[76:91], v[128:131], v[132:135], v[76:91]
	ds_read_b128 v[128:131], v216 offset:160
	ds_read_b128 v[132:135], v217 offset:34976
	s_waitcnt lgkmcnt(6)
	v_mfma_f32_32x32x16_bf16 v[76:91], v[140:143], v[144:147], v[76:91]
	ds_read_b128 v[140:143], v216 offset:192
	ds_read_b128 v[144:147], v217 offset:35008
	s_waitcnt lgkmcnt(6)
	v_mfma_f32_32x32x16_bf16 v[76:91], v[152:155], v[156:159], v[76:91]
	ds_read_b128 v[152:155], v216 offset:224
	ds_read_b128 v[156:159], v217 offset:35040
	s_waitcnt lgkmcnt(6)
	v_mfma_f32_32x32x16_bf16 v[76:91], v[116:119], v[120:123], v[76:91]
	ds_read_b128 v[234:237], v222 offset:2048
	ds_read_b128 v[238:241], v222 offset:2080
	ds_read_b128 v[242:245], v222 offset:2112
	ds_read_b128 v[246:249], v222 offset:2144
	ds_read_b32 v250, v223 offset:2048
	s_waitcnt lgkmcnt(9)
	v_mfma_f32_32x32x16_bf16 v[76:91], v[128:131], v[132:135], v[76:91]
	s_waitcnt lgkmcnt(7)
	v_mfma_f32_32x32x16_bf16 v[76:91], v[140:143], v[144:147], v[76:91]
	s_waitcnt lgkmcnt(5)
	v_mfma_f32_32x32x16_bf16 v[76:91], v[152:155], v[156:159], v[76:91]
	s_cmp_lt_u32 s3, 4
	s_cbranch_scc0 .Lm_w456_34
	ds_read_b128 v[176:179], v173 offset:0
	ds_read_b128 v[180:183], v173 offset:32
	ds_read_b128 v[184:187], v173 offset:64
	ds_read_b128 v[188:191], v173 offset:96
	ds_read_b128 v[192:195], v173 offset:128
	ds_read_b128 v[196:199], v173 offset:160
	ds_read_b128 v[200:203], v173 offset:192
	ds_read_b128 v[204:207], v173 offset:224
	ds_read_b32 v2, v211 offset:2048
	s_waitcnt lgkmcnt(9)
	v_sub_f32_e32 v116, v234, v250
	v_sub_f32_e32 v117, v235, v250
	v_sub_f32_e32 v118, v236, v250
	v_sub_f32_e32 v119, v237, v250
	v_sub_f32_e32 v120, v238, v250
	v_sub_f32_e32 v121, v239, v250
	v_sub_f32_e32 v122, v240, v250
	v_sub_f32_e32 v123, v241, v250
	v_sub_f32_e32 v124, v242, v250
	v_sub_f32_e32 v125, v243, v250
	v_sub_f32_e32 v126, v244, v250
	v_sub_f32_e32 v127, v245, v250
	v_sub_f32_e32 v128, v246, v250
	v_sub_f32_e32 v129, v247, v250
	v_sub_f32_e32 v130, v248, v250
	v_sub_f32_e32 v131, v249, v250
	v_exp_f32_e32 v116, v116
	v_exp_f32_e32 v117, v117
	v_exp_f32_e32 v118, v118
	v_exp_f32_e32 v119, v119
	v_exp_f32_e32 v120, v120
	v_exp_f32_e32 v121, v121
	v_exp_f32_e32 v122, v122
	v_exp_f32_e32 v123, v123
	v_exp_f32_e32 v124, v124
	v_exp_f32_e32 v125, v125
	v_exp_f32_e32 v126, v126
	v_exp_f32_e32 v127, v127
	v_exp_f32_e32 v128, v128
	v_exp_f32_e32 v129, v129
	v_exp_f32_e32 v130, v130
	v_exp_f32_e32 v131, v131
	v_mul_f32_e32 v76, v76, v116
	v_mul_f32_e32 v77, v77, v117
	v_mul_f32_e32 v78, v78, v118
	v_mul_f32_e32 v79, v79, v119
	v_mul_f32_e32 v80, v80, v120
	v_mul_f32_e32 v81, v81, v121
	v_mul_f32_e32 v82, v82, v122
	v_mul_f32_e32 v83, v83, v123
	v_mul_f32_e32 v84, v84, v124
	v_mul_f32_e32 v85, v85, v125
	v_mul_f32_e32 v86, v86, v126
	v_mul_f32_e32 v87, v87, v127
	v_mul_f32_e32 v88, v88, v128
	v_mul_f32_e32 v89, v89, v129
	v_mul_f32_e32 v90, v90, v130
	v_mul_f32_e32 v91, v91, v131
	s_cmp_eq_u32 s53, 0
	s_cbranch_scc1 .Lm_nodiag_35
	v_cndmask_b32_e64 v76, 0, v76, s[64:65]
	v_cndmask_b32_e64 v77, 0, v77, s[66:67]
	v_cndmask_b32_e64 v78, 0, v78, s[68:69]
	v_cndmask_b32_e64 v79, 0, v79, s[70:71]
	v_cndmask_b32_e64 v80, 0, v80, s[72:73]
	v_cndmask_b32_e64 v81, 0, v81, s[74:75]
	v_cndmask_b32_e64 v82, 0, v82, s[76:77]
	v_cndmask_b32_e64 v83, 0, v83, s[78:79]
	v_cndmask_b32_e64 v84, 0, v84, s[80:81]
	v_cndmask_b32_e64 v85, 0, v85, s[82:83]
	v_cndmask_b32_e64 v86, 0, v86, s[84:85]
	v_cndmask_b32_e64 v87, 0, v87, s[86:87]
	v_cndmask_b32_e64 v88, 0, v88, s[88:89]
	v_cndmask_b32_e64 v89, 0, v89, s[90:91]
	v_cndmask_b32_e64 v90, 0, v90, s[92:93]
	v_cndmask_b32_e64 v91, 0, v91, s[94:95]

.Lm_w456_34:
	s_waitcnt lgkmcnt(0)
	ds_read_b32 v1, v172 offset:2048
	ds_read_b64_tr_b16 v[116:117], v193 offset:0
	ds_read_b64_tr_b16 v[118:119], v193 offset:1088
	ds_read_b64_tr_b16 v[120:121], v192 offset:0
	ds_read_b64_tr_b16 v[122:123], v192 offset:320
	ds_read_b64_tr_b16 v[124:125], v193 offset:4352
	ds_read_b64_tr_b16 v[126:127], v193 offset:5440
	ds_read_b64_tr_b16 v[128:129], v192 offset:1280
	ds_read_b64_tr_b16 v[130:131], v192 offset:1600
	ds_read_b64_tr_b16 v[132:133], v193 offset:8704
	ds_read_b64_tr_b16 v[134:135], v193 offset:9792
	ds_read_b64_tr_b16 v[136:137], v192 offset:2560
	ds_read_b64_tr_b16 v[138:139], v192 offset:2880
	s_waitcnt lgkmcnt(12)
	v_exp_f32_e32 v1, v1
	s_nop 0
	v_mul_f32_e32 v176, v176, v1
	v_mul_f32_e32 v177, v177, v1
	v_mul_f32_e32 v178, v178, v1
	v_mul_f32_e32 v179, v179, v1
	v_mul_f32_e32 v180, v180, v1
	v_mul_f32_e32 v181, v181, v1
	v_mul_f32_e32 v182, v182, v1
	v_mul_f32_e32 v183, v183, v1
	v_mul_f32_e32 v184, v184, v1
	v_mul_f32_e32 v185, v185, v1
	v_mul_f32_e32 v186, v186, v1
	v_mul_f32_e32 v187, v187, v1
	v_mul_f32_e32 v188, v188, v1
	v_mul_f32_e32 v189, v189, v1
	v_mul_f32_e32 v190, v190, v1
	v_mul_f32_e32 v191, v191, v1
	s_nop 1
	s_waitcnt lgkmcnt(8)
	v_mfma_f32_32x32x16_bf16 v[176:191], v[116:119], v[120:123], v[176:191]
	ds_read_b64_tr_b16 v[116:117], v193 offset:13056
	ds_read_b64_tr_b16 v[118:119], v193 offset:14144
	ds_read_b64_tr_b16 v[120:121], v192 offset:3840
	ds_read_b64_tr_b16 v[122:123], v192 offset:4160
	s_waitcnt lgkmcnt(8)
	v_mfma_f32_32x32x16_bf16 v[176:191], v[124:127], v[128:131], v[176:191]
	ds_read_b64_tr_b16 v[124:125], v193 offset:17408
	ds_read_b64_tr_b16 v[126:127], v193 offset:18496
	ds_read_b64_tr_b16 v[128:129], v192 offset:5120
	ds_read_b64_tr_b16 v[130:131], v192 offset:5440
	s_waitcnt lgkmcnt(8)
	v_mfma_f32_32x32x16_bf16 v[176:191], v[132:135], v[136:139], v[176:191]
	ds_read_b64_tr_b16 v[132:133], v193 offset:21760
	ds_read_b64_tr_b16 v[134:135], v193 offset:22848
	ds_read_b64_tr_b16 v[136:137], v192 offset:6400
	ds_read_b64_tr_b16 v[138:139], v192 offset:6720
	s_waitcnt lgkmcnt(8)
	v_mfma_f32_32x32x16_bf16 v[176:191], v[116:119], v[120:123], v[176:191]
	ds_read_b64_tr_b16 v[116:117], v193 offset:26112
	ds_read_b64_tr_b16 v[118:119], v193 offset:27200
	ds_read_b64_tr_b16 v[120:121], v192 offset:7680
	ds_read_b64_tr_b16 v[122:123], v192 offset:8000
	s_waitcnt lgkmcnt(8)
	v_mfma_f32_32x32x16_bf16 v[176:191], v[124:127], v[128:131], v[176:191]
	ds_read_b64_tr_b16 v[124:125], v193 offset:30464
	ds_read_b64_tr_b16 v[126:127], v193 offset:31552
	ds_read_b64_tr_b16 v[128:129], v192 offset:8960
	ds_read_b64_tr_b16 v[130:131], v192 offset:9280
	s_waitcnt lgkmcnt(8)
	v_mfma_f32_32x32x16_bf16 v[176:191], v[132:135], v[136:139], v[176:191]
	s_waitcnt lgkmcnt(4)
	v_mfma_f32_32x32x16_bf16 v[176:191], v[116:119], v[120:123], v[176:191]
	s_waitcnt lgkmcnt(0)
	v_mfma_f32_32x32x16_bf16 v[176:191], v[124:127], v[128:131], v[176:191]
	v_sub_f32_e32 v116, v234, v250
	v_sub_f32_e32 v117, v235, v250
	v_sub_f32_e32 v118, v236, v250
	v_sub_f32_e32 v119, v237, v250
	v_sub_f32_e32 v120, v238, v250
	v_sub_f32_e32 v121, v239, v250
	v_sub_f32_e32 v122, v240, v250
	v_sub_f32_e32 v123, v241, v250
	v_sub_f32_e32 v124, v242, v250
	v_sub_f32_e32 v125, v243, v250
	v_sub_f32_e32 v126, v244, v250
	v_sub_f32_e32 v127, v245, v250
	v_sub_f32_e32 v128, v246, v250
	v_sub_f32_e32 v129, v247, v250
	v_sub_f32_e32 v130, v248, v250
	v_sub_f32_e32 v131, v249, v250
	v_exp_f32_e32 v116, v116
	v_exp_f32_e32 v117, v117
	v_exp_f32_e32 v118, v118
	v_exp_f32_e32 v119, v119
	v_exp_f32_e32 v120, v120
	v_exp_f32_e32 v121, v121
	v_exp_f32_e32 v122, v122
	v_exp_f32_e32 v123, v123
	v_exp_f32_e32 v124, v124
	v_exp_f32_e32 v125, v125
	v_exp_f32_e32 v126, v126
	v_exp_f32_e32 v127, v127
	v_exp_f32_e32 v128, v128
	v_exp_f32_e32 v129, v129
	v_exp_f32_e32 v130, v130
	v_exp_f32_e32 v131, v131
	v_mul_f32_e32 v76, v76, v116
	v_mul_f32_e32 v77, v77, v117
	v_mul_f32_e32 v78, v78, v118
	v_mul_f32_e32 v79, v79, v119
	v_mul_f32_e32 v80, v80, v120
	v_mul_f32_e32 v81, v81, v121
	v_mul_f32_e32 v82, v82, v122
	v_mul_f32_e32 v83, v83, v123
	v_mul_f32_e32 v84, v84, v124
	v_mul_f32_e32 v85, v85, v125
	v_mul_f32_e32 v86, v86, v126
	v_mul_f32_e32 v87, v87, v127
	v_mul_f32_e32 v88, v88, v128
	v_mul_f32_e32 v89, v89, v129
	v_mul_f32_e32 v90, v90, v130
	v_mul_f32_e32 v91, v91, v131
	s_cmp_eq_u32 s53, 0
	s_cbranch_scc1 .Lm_nodiag_36
	v_cndmask_b32_e64 v76, 0, v76, s[64:65]
	v_cndmask_b32_e64 v77, 0, v77, s[66:67]
	v_cndmask_b32_e64 v78, 0, v78, s[68:69]
	v_cndmask_b32_e64 v79, 0, v79, s[70:71]
	v_cndmask_b32_e64 v80, 0, v80, s[72:73]
	v_cndmask_b32_e64 v81, 0, v81, s[74:75]
	v_cndmask_b32_e64 v82, 0, v82, s[76:77]
	v_cndmask_b32_e64 v83, 0, v83, s[78:79]
	v_cndmask_b32_e64 v84, 0, v84, s[80:81]
	v_cndmask_b32_e64 v85, 0, v85, s[82:83]
	v_cndmask_b32_e64 v86, 0, v86, s[84:85]
	v_cndmask_b32_e64 v87, 0, v87, s[86:87]
	v_cndmask_b32_e64 v88, 0, v88, s[88:89]
	v_cndmask_b32_e64 v89, 0, v89, s[90:91]
	v_cndmask_b32_e64 v90, 0, v90, s[92:93]
	v_cndmask_b32_e64 v91, 0, v91, s[94:95]
.Lm_nodiag_36:
	v_cvt_pk_bf16_f32 v132, v76, v77
	v_cvt_pk_bf16_f32 v133, v78, v79
	v_cvt_pk_bf16_f32 v134, v80, v81
	v_cvt_pk_bf16_f32 v135, v82, v83
	v_cvt_pk_bf16_f32 v136, v84, v85
	v_cvt_pk_bf16_f32 v137, v86, v87
	v_cvt_pk_bf16_f32 v138, v88, v89
	v_cvt_pk_bf16_f32 v139, v90, v91
	ds_write_b64 v224, v[132:133] offset:0
	ds_write_b64 v224, v[134:135] offset:16
	ds_write_b64 v224, v[136:137] offset:32
	ds_write_b64 v224, v[138:139] offset:48
	v_cvt_pk_bf16_f32 v140, v176, v177
	v_cvt_pk_bf16_f32 v141, v178, v179
	v_cvt_pk_bf16_f32 v142, v180, v181
	v_cvt_pk_bf16_f32 v143, v182, v183
	v_cvt_pk_bf16_f32 v144, v184, v185
	v_cvt_pk_bf16_f32 v145, v186, v187
	v_cvt_pk_bf16_f32 v146, v188, v189
	v_cvt_pk_bf16_f32 v147, v190, v191
	ds_write_b64 v194, v[140:141] offset:0
	ds_write_b64 v194, v[142:143] offset:16
	ds_write_b64 v194, v[144:145] offset:32
	ds_write_b64 v194, v[146:147] offset:48
	s_branch .Lm_adone_31
.Lm_g0_28:
	ds_read_b32 v1, v172 offset:2048
	ds_read_b64_tr_b16 v[116:117], v193 offset:0
	ds_read_b64_tr_b16 v[118:119], v193 offset:1088
	ds_read_b64_tr_b16 v[120:121], v192 offset:0
	ds_read_b64_tr_b16 v[122:123], v192 offset:320
	ds_read_b64_tr_b16 v[124:125], v193 offset:4352
	ds_read_b64_tr_b16 v[126:127], v193 offset:5440
	ds_read_b64_tr_b16 v[128:129], v192 offset:1280
	ds_read_b64_tr_b16 v[130:131], v192 offset:1600
	ds_read_b64_tr_b16 v[132:133], v193 offset:8704
	ds_read_b64_tr_b16 v[134:135], v193 offset:9792
	ds_read_b64_tr_b16 v[136:137], v192 offset:2560
	ds_read_b64_tr_b16 v[138:139], v192 offset:2880
	s_waitcnt lgkmcnt(12)
	v_exp_f32_e32 v1, v1
	s_nop 0
	v_mul_f32_e32 v176, v176, v1
	v_mul_f32_e32 v177, v177, v1
	v_mul_f32_e32 v178, v178, v1
	v_mul_f32_e32 v179, v179, v1
	v_mul_f32_e32 v180, v180, v1
	v_mul_f32_e32 v181, v181, v1
	v_mul_f32_e32 v182, v182, v1
	v_mul_f32_e32 v183, v183, v1
	v_mul_f32_e32 v184, v184, v1
	v_mul_f32_e32 v185, v185, v1
	v_mul_f32_e32 v186, v186, v1
	v_mul_f32_e32 v187, v187, v1
	v_mul_f32_e32 v188, v188, v1
	v_mul_f32_e32 v189, v189, v1
	v_mul_f32_e32 v190, v190, v1
	v_mul_f32_e32 v191, v191, v1
	s_nop 1
	s_waitcnt lgkmcnt(8)
	v_mfma_f32_32x32x16_bf16 v[176:191], v[116:119], v[120:123], v[176:191]
	ds_read_b64_tr_b16 v[116:117], v193 offset:13056
	ds_read_b64_tr_b16 v[118:119], v193 offset:14144
	ds_read_b64_tr_b16 v[120:121], v192 offset:3840
	ds_read_b64_tr_b16 v[122:123], v192 offset:4160
	s_waitcnt lgkmcnt(8)
	v_mfma_f32_32x32x16_bf16 v[176:191], v[124:127], v[128:131], v[176:191]
	ds_read_b64_tr_b16 v[124:125], v193 offset:17408
	ds_read_b64_tr_b16 v[126:127], v193 offset:18496
	ds_read_b64_tr_b16 v[128:129], v192 offset:5120
	ds_read_b64_tr_b16 v[130:131], v192 offset:5440
	s_waitcnt lgkmcnt(8)
	v_mfma_f32_32x32x16_bf16 v[176:191], v[132:135], v[136:139], v[176:191]
	ds_read_b64_tr_b16 v[132:133], v193 offset:21760
	ds_read_b64_tr_b16 v[134:135], v193 offset:22848
	ds_read_b64_tr_b16 v[136:137], v192 offset:6400
	ds_read_b64_tr_b16 v[138:139], v192 offset:6720
	s_waitcnt lgkmcnt(8)
	v_mfma_f32_32x32x16_bf16 v[176:191], v[116:119], v[120:123], v[176:191]
	ds_read_b64_tr_b16 v[116:117], v193 offset:26112
	ds_read_b64_tr_b16 v[118:119], v193 offset:27200
	ds_read_b64_tr_b16 v[120:121], v192 offset:7680
	ds_read_b64_tr_b16 v[122:123], v192 offset:8000
	s_waitcnt lgkmcnt(8)
	v_mfma_f32_32x32x16_bf16 v[176:191], v[124:127], v[128:131], v[176:191]
	ds_read_b64_tr_b16 v[124:125], v193 offset:30464
	ds_read_b64_tr_b16 v[126:127], v193 offset:31552
	ds_read_b64_tr_b16 v[128:129], v192 offset:8960
	ds_read_b64_tr_b16 v[130:131], v192 offset:9280
	s_waitcnt lgkmcnt(8)
	v_mfma_f32_32x32x16_bf16 v[176:191], v[132:135], v[136:139], v[176:191]
	s_waitcnt lgkmcnt(4)
	v_mfma_f32_32x32x16_bf16 v[176:191], v[116:119], v[120:123], v[176:191]
	s_waitcnt lgkmcnt(0)
	v_mfma_f32_32x32x16_bf16 v[176:191], v[124:127], v[128:131], v[176:191]
	s_nop 7
	s_nop 3
	v_cvt_pk_bf16_f32 v140, v176, v177
	v_cvt_pk_bf16_f32 v141, v178, v179
	v_cvt_pk_bf16_f32 v142, v180, v181
	v_cvt_pk_bf16_f32 v143, v182, v183
	v_cvt_pk_bf16_f32 v144, v184, v185
	v_cvt_pk_bf16_f32 v145, v186, v187
	v_cvt_pk_bf16_f32 v146, v188, v189
	v_cvt_pk_bf16_f32 v147, v190, v191
	ds_write_b64 v194, v[140:141] offset:0
	ds_write_b64 v194, v[142:143] offset:16
	ds_write_b64 v194, v[144:145] offset:32
	ds_write_b64 v194, v[146:147] offset:48
	s_cmp_lt_u32 s50, 63
	s_cbranch_scc0 .Lm_noscan_37
	s_cmp_lt_u32 s50, 62
	s_cbranch_scc0 .Lm_sc0_38
	s_waitcnt vmcnt(9)
	s_branch .Lm_scgo_39

.Lm_scanf_40:
	v_mul_f32_e32 v122, 0x3fb8aa3b, v122
	v_mul_f32_e32 v123, 0x3fb8aa3b, v123
	v_mul_f32_e32 v120, 0x3fb8aa3b, v120
	ds_write_b64 v196, v[122:123] offset:0
	ds_write_b64 v196, v[204:205] offset:512
	ds_write_b32 v172, v120 offset:0
	s_cmp_lt_u32 s50, 62
	s_cbranch_scc0 .Lm_noscan_37
	s_waitcnt lgkmcnt(0)
	global_load_dword v204, v195, s[42:43]
	global_load_dword v205, v195, s[42:43] offset:256
	s_add_u32 s42, s42, s48
	s_addc_u32 s43, s43, s55
.Lm_noscan_37:
.Lm_adone_31:
	s_waitcnt lgkmcnt(0)
	s_barrier
	s_cmp_lt_u32 s3, 4
	s_cbranch_scc0 .Lm_noy_41
	ds_read_b64_tr_b16 v[116:117], v208 offset:43008
	ds_read_b64_tr_b16 v[118:119], v208 offset:43328
	ds_read_b64_tr_b16 v[120:121], v209 offset:0
	ds_read_b64_tr_b16 v[122:123], v209 offset:1088
	ds_read_b128 v[124:127], v210 offset:8704
	ds_read_b64_tr_b16 v[128:129], v208 offset:44288
	ds_read_b64_tr_b16 v[130:131], v208 offset:44608
	ds_read_b64_tr_b16 v[132:133], v209 offset:4352
	ds_read_b64_tr_b16 v[134:135], v209 offset:5440
	ds_read_b128 v[136:139], v210 offset:8736
	ds_read_b64_tr_b16 v[140:141], v208 offset:45568
	ds_read_b64_tr_b16 v[142:143], v208 offset:45888
	ds_read_b64_tr_b16 v[144:145], v209 offset:8704
	ds_read_b64_tr_b16 v[146:147], v209 offset:9792
	ds_read_b128 v[148:151], v210 offset:8768
	s_waitcnt lgkmcnt(10)
	v_mfma_f32_32x32x16_bf16 v[76:91], v[116:119], v[120:123], 0
	v_mfma_f32_32x32x16_bf16 v[92:107], v[124:127], v[176:179], 0
	ds_read_b64_tr_b16 v[116:117], v208 offset:46848
	ds_read_b64_tr_b16 v[118:119], v208 offset:47168
	ds_read_b64_tr_b16 v[120:121], v209 offset:13056
	ds_read_b64_tr_b16 v[122:123], v209 offset:14144
	ds_read_b128 v[124:127], v210 offset:8800
	s_waitcnt lgkmcnt(10)
	v_mfma_f32_32x32x16_bf16 v[76:91], v[128:131], v[132:135], v[76:91]
	v_mfma_f32_32x32x16_bf16 v[92:107], v[136:139], v[180:183], v[92:107]
	ds_read_b64_tr_b16 v[128:129], v208 offset:48128
	ds_read_b64_tr_b16 v[130:131], v208 offset:48448
	ds_read_b64_tr_b16 v[132:133], v209 offset:17408
	ds_read_b64_tr_b16 v[134:135], v209 offset:18496
	ds_read_b128 v[136:139], v210 offset:8832
	s_waitcnt lgkmcnt(10)
	v_mfma_f32_32x32x16_bf16 v[76:91], v[140:143], v[144:147], v[76:91]
	v_mfma_f32_32x32x16_bf16 v[92:107], v[148:151], v[184:187], v[92:107]
	ds_read_b64_tr_b16 v[140:141], v208 offset:49408
	ds_read_b64_tr_b16 v[142:143], v208 offset:49728
	ds_read_b64_tr_b16 v[144:145], v209 offset:21760
	ds_read_b64_tr_b16 v[146:147], v209 offset:22848
	ds_read_b128 v[148:151], v210 offset:8864
	s_waitcnt lgkmcnt(10)
	v_mfma_f32_32x32x16_bf16 v[76:91], v[116:119], v[120:123], v[76:91]
	v_mfma_f32_32x32x16_bf16 v[92:107], v[124:127], v[188:191], v[92:107]
	ds_read_b64_tr_b16 v[116:117], v208 offset:50688
	ds_read_b64_tr_b16 v[118:119], v208 offset:51008
	ds_read_b64_tr_b16 v[120:121], v209 offset:26112
	ds_read_b64_tr_b16 v[122:123], v209 offset:27200
	ds_read_b128 v[124:127], v210 offset:8896
	s_waitcnt lgkmcnt(10)
	v_mfma_f32_32x32x16_bf16 v[76:91], v[128:131], v[132:135], v[76:91]
	v_mfma_f32_32x32x16_bf16 v[92:107], v[136:139], v[192:195], v[92:107]
	ds_read_b64_tr_b16 v[128:129], v208 offset:51968
	ds_read_b64_tr_b16 v[130:131], v208 offset:52288
	ds_read_b64_tr_b16 v[132:133], v209 offset:30464
	ds_read_b64_tr_b16 v[134:135], v209 offset:31552
	ds_read_b128 v[136:139], v210 offset:8928
	s_waitcnt lgkmcnt(10)
	v_mfma_f32_32x32x16_bf16 v[76:91], v[140:143], v[144:147], v[76:91]
	v_mfma_f32_32x32x16_bf16 v[92:107], v[148:151], v[196:199], v[92:107]
	s_waitcnt lgkmcnt(5)
	v_mfma_f32_32x32x16_bf16 v[76:91], v[116:119], v[120:123], v[76:91]
	v_mfma_f32_32x32x16_bf16 v[92:107], v[124:127], v[200:203], v[92:107]
	s_waitcnt lgkmcnt(0)
	v_mfma_f32_32x32x16_bf16 v[76:91], v[128:131], v[132:135], v[76:91]
	v_mfma_f32_32x32x16_bf16 v[92:107], v[136:139], v[204:207], v[92:107]

.Lm_wgo_44:
	ds_read_b32 v116, v172 offset:0
	ds_read_b32 v117, v171 offset:0
	ds_read_b32 v118, v171 offset:512
	ds_write_b128 v169, v[20:23] offset:0
	ds_write_b128 v169, v[4:7] offset:34816
	ds_write_b128 v169, v[24:27] offset:8704
	ds_write_b128 v169, v[8:11] offset:43520
	ds_write_b128 v169, v[28:31] offset:17408
	ds_write_b128 v169, v[12:15] offset:52224
	ds_write_b128 v169, v[32:35] offset:26112
	ds_write_b128 v169, v[16:19] offset:60928
	v_lshlrev_b32_e32 v120, 16, v36
	v_and_b32_e32 v121, 0xffff0000, v36
	v_lshlrev_b32_e32 v122, 16, v37
	v_and_b32_e32 v123, 0xffff0000, v37
	v_lshlrev_b32_e32 v124, 16, v38
	v_and_b32_e32 v125, 0xffff0000, v38
	v_lshlrev_b32_e32 v126, 16, v39
	v_and_b32_e32 v127, 0xffff0000, v39
	s_waitcnt lgkmcnt(8)
	v_sub_f32_e32 v119, v116, v117
	v_exp_f32_e32 v119, v119
	v_mul_f32_e32 v128, v118, v120
	v_mul_f32_e32 v129, v118, v121
	v_mul_f32_e32 v130, v118, v122
	v_mul_f32_e32 v131, v118, v123
	v_mul_f32_e32 v132, v118, v124
	v_mul_f32_e32 v133, v118, v125
	v_mul_f32_e32 v134, v118, v126
	v_mul_f32_e32 v135, v118, v127
	v_mul_f32_e32 v119, v118, v119
	v_cvt_pk_bf16_f32 v144, v128, v129
	v_cvt_pk_bf16_f32 v145, v130, v131
	v_cvt_pk_bf16_f32 v146, v132, v133
	v_cvt_pk_bf16_f32 v147, v134, v135
	v_mul_f32_e32 v136, v119, v120
	v_mul_f32_e32 v137, v119, v121
	v_mul_f32_e32 v138, v119, v122
	v_mul_f32_e32 v139, v119, v123
	v_mul_f32_e32 v140, v119, v124
	v_mul_f32_e32 v141, v119, v125
	v_mul_f32_e32 v142, v119, v126
	v_mul_f32_e32 v143, v119, v127
	v_cvt_pk_bf16_f32 v148, v136, v137
	v_cvt_pk_bf16_f32 v149, v138, v139
	v_cvt_pk_bf16_f32 v150, v140, v141
	v_cvt_pk_bf16_f32 v151, v142, v143
	ds_write_b128 v170, v[144:147] offset:0
	ds_write_b128 v170, v[148:151] offset:10240

.Lm_noy2_45:
	s_add_u32 s44, s44, s49
	s_addc_u32 s45, s45, s55
	s_waitcnt lgkmcnt(0)
	s_cmp_lt_u32 s50, 61
	s_cbranch_scc0 .Lm_nold_46
	global_load_dwordx4 v[4:7], v164, s[38:39]
	global_load_dwordx4 v[20:23], v164, s[38:39] offset:256
	global_load_dwordx4 v[8:11], v165, s[38:39]
	global_load_dwordx4 v[24:27], v165, s[38:39] offset:256
	global_load_dwordx4 v[12:15], v166, s[38:39]
	global_load_dwordx4 v[28:31], v166, s[38:39] offset:256
	global_load_dwordx4 v[16:19], v167, s[38:39]
	global_load_dwordx4 v[32:35], v167, s[38:39] offset:256
	global_load_dwordx4 v[36:39], v168, s[40:41]
	s_add_u32 s38, s38, s46
	s_addc_u32 s39, s39, s55
	s_add_u32 s40, s40, s47
	s_addc_u32 s41, s41, s55
.Lm_nold_46:
	s_barrier
	s_add_u32 s50, s50, 1
	s_cmp_lt_u32 s50, 64
	s_cbranch_scc1 .Lm_loop
	s_waitcnt vmcnt(0)
	s_add_u32 s61, s61, s58
	s_cmpk_gt_i32 s61, 0xff
	s_cbranch_scc0 .Lm_item
	s_mov_b32 s77, 0x800000

	.amdhsa_kernel _Z8mega_fwd4Args
		.amdhsa_group_segment_fixed_size 157696
		.amdhsa_private_segment_fixed_size 0
		.amdhsa_kernarg_size 1984
		.amdhsa_user_sgpr_count 2
		.amdhsa_user_sgpr_dispatch_ptr 0
		.amdhsa_user_sgpr_queue_ptr 0
		.amdhsa_user_sgpr_kernarg_segment_ptr 1
		.amdhsa_user_sgpr_dispatch_id 0
		.amdhsa_user_sgpr_kernarg_preload_length 0
		.amdhsa_user_sgpr_kernarg_preload_offset 0
		.amdhsa_user_sgpr_private_segment_size 0
		.amdhsa_uses_dynamic_stack 0
		.amdhsa_enable_private_segment 0
		.amdhsa_system_sgpr_workgroup_id_x 1
		.amdhsa_system_sgpr_workgroup_id_y 0
		.amdhsa_system_sgpr_workgroup_id_z 0
		.amdhsa_system_sgpr_workgroup_info 0
		.amdhsa_system_vgpr_workitem_id 2
		.amdhsa_next_free_vgpr 256
		.amdhsa_next_free_sgpr 100
		.amdhsa_accum_offset 256
		.amdhsa_reserve_vcc 1
		.amdhsa_float_round_mode_32 0
		.amdhsa_float_round_mode_16_64 0
		.amdhsa_float_denorm_mode_32 3
		.amdhsa_float_denorm_mode_16_64 3
		.amdhsa_dx10_clamp 1
		.amdhsa_ieee_mode 1
		.amdhsa_fp16_overflow 0
		.amdhsa_tg_split 0
		.amdhsa_exception_fp_ieee_invalid_op 0
		.amdhsa_exception_fp_denorm_src 0
		.amdhsa_exception_fp_ieee_div_zero 0
		.amdhsa_exception_fp_ieee_overflow 0
		.amdhsa_exception_fp_ieee_underflow 0
		.amdhsa_exception_fp_ieee_inexact 0
		.amdhsa_exception_int_div_zero 0
	.end_amdhsa_kernel

amdhsa.kernels:
  - .agpr_count:     0
    .args:
      - .offset:         0
        .size:           1728
        .value_kind:     by_value
      - .offset:         1728
        .size:           4
        .value_kind:     hidden_block_count_x
      - .offset:         1732
        .size:           4
        .value_kind:     hidden_block_count_y
      - .offset:         1736
        .size:           4
        .value_kind:     hidden_block_count_z
      - .offset:         1740
        .size:           2
        .value_kind:     hidden_group_size_x
      - .offset:         1742
        .size:           2
        .value_kind:     hidden_group_size_y
      - .offset:         1744
        .size:           2
        .value_kind:     hidden_group_size_z
      - .offset:         1746
        .size:           2
        .value_kind:     hidden_remainder_x
      - .offset:         1748
        .size:           2
        .value_kind:     hidden_remainder_y
      - .offset:         1750
        .size:           2
        .value_kind:     hidden_remainder_z
      - .offset:         1768
        .size:           8
        .value_kind:     hidden_global_offset_x
      - .offset:         1776
        .size:           8
        .value_kind:     hidden_global_offset_y
      - .offset:         1784
        .size:           8
        .value_kind:     hidden_global_offset_z
      - .offset:         1792
        .size:           2
        .value_kind:     hidden_grid_dims
      - .offset:         1816
        .size:           8
        .value_kind:     hidden_multigrid_sync_arg
    .group_segment_fixed_size: 157696
    .kernarg_segment_align: 8
    .kernarg_segment_size: 1984
    .language:       OpenCL C
    .language_version:
      - 2
      - 0
    .max_flat_workgroup_size: 512
    .name:           _Z8mega_fwd4Args
    .private_segment_fixed_size: 0
    .sgpr_count:     106
    .sgpr_spill_count: 165
    .symbol:         _Z8mega_fwd4Args.kd
    .uniform_work_group_size: 1
    .uses_dynamic_stack: false
    .vgpr_count:     256
    .vgpr_spill_count: 0
    .wavefront_size: 64
